# ctx small-GEMM K loops rewritten straight-line with 16-32 k-steps of weight-fragment loads in flight (was 4 per round trip)
# speedup vs baseline: 1.0091x; 1.0004x over previous
; #define LAS __attribute__((address_space(3)))
; template <int MODE>
; __device__ __forceinline__ void ctx_small_gemm(PREF P, unsigned char* shm) {
;     ...
; #pragma unroll 4
;             for (int ks = 0; ks < KS; ++ks) {
;                 const bf16x8 a0 = *(const LAS bf16x8*)(lds + (rt0 * 16 + r) * (K * 2) + (((ks * 4 + q) ^ r) << 4));
;                 const bf16x8 b0 = *(const bf16x8*)(W0 + ks * 32);
;                 if (MODE == 0) { const bf16x8 b1 = *(const bf16x8*)(W1 + ks * 32);
;                     acc0 = __builtin_amdgcn_mfma_f32_16x16x32_bf16(a0, b0, acc0, 0, 0, 0); acc1 = __builtin_amdgcn_mfma_f32_16x16x32_bf16(a0, b1, acc1, 0, 0, 0); }
.LBB0_718:
	v_xor_b32_e32 v56, v17, v16
	v_lshl_add_u32 v57, v56, 4, v19
	v_add_u32_e32 v56, 4, v17
	v_xor_b32_e32 v56, v56, v16
	v_lshl_add_u32 v58, v56, 4, v19
	v_add_u32_e32 v56, 8, v17
	v_xor_b32_e32 v56, v56, v16
	v_lshl_add_u32 v59, v56, 4, v19
	v_add_u32_e32 v56, 12, v17
	v_xor_b32_e32 v56, v56, v16
	v_lshl_add_u32 v60, v56, 4, v19
	v_add_co_u32_e32 v62, vcc, s10, v14
	v_addc_co_u32_e32 v63, vcc, 0, v15, vcc
	v_add_co_u32_e32 v64, vcc, s11, v14
	v_addc_co_u32_e32 v65, vcc, 0, v15, vcc
	global_load_dwordx4 v[66:69], v[62:63], off
	global_load_dwordx4 v[70:73], v[64:65], off
	global_load_dwordx4 v[74:77], v[62:63], off offset:64
	global_load_dwordx4 v[78:81], v[64:65], off offset:64
	global_load_dwordx4 v[82:85], v[62:63], off offset:128
	global_load_dwordx4 v[86:89], v[64:65], off offset:128
	global_load_dwordx4 v[90:93], v[62:63], off offset:192
	global_load_dwordx4 v[94:97], v[64:65], off offset:192
	global_load_dwordx4 v[98:101], v[62:63], off offset:256
	global_load_dwordx4 v[102:105], v[64:65], off offset:256
	global_load_dwordx4 v[106:109], v[62:63], off offset:320
	global_load_dwordx4 v[110:113], v[64:65], off offset:320
	global_load_dwordx4 v[114:117], v[62:63], off offset:384
	global_load_dwordx4 v[118:121], v[64:65], off offset:384
	global_load_dwordx4 v[122:125], v[62:63], off offset:448
	global_load_dwordx4 v[126:129], v[64:65], off offset:448
	global_load_dwordx4 v[130:133], v[62:63], off offset:512
	global_load_dwordx4 v[134:137], v[64:65], off offset:512
	global_load_dwordx4 v[138:141], v[62:63], off offset:576
	global_load_dwordx4 v[142:145], v[64:65], off offset:576
	global_load_dwordx4 v[146:149], v[62:63], off offset:640
	global_load_dwordx4 v[150:153], v[64:65], off offset:640
	global_load_dwordx4 v[154:157], v[62:63], off offset:704
	global_load_dwordx4 v[158:161], v[64:65], off offset:704
	global_load_dwordx4 v[162:165], v[62:63], off offset:768
	global_load_dwordx4 v[166:169], v[64:65], off offset:768
	global_load_dwordx4 v[170:173], v[62:63], off offset:832
	global_load_dwordx4 v[174:177], v[64:65], off offset:832
	global_load_dwordx4 v[178:181], v[62:63], off offset:896
	global_load_dwordx4 v[182:185], v[64:65], off offset:896
	global_load_dwordx4 v[186:189], v[62:63], off offset:960
	global_load_dwordx4 v[190:193], v[64:65], off offset:960
	ds_read_b128 v[194:197], v57
	ds_read_b128 v[198:201], v58
	ds_read_b128 v[202:205], v59
	ds_read_b128 v[206:209], v60
	ds_read_b128 v[210:213], v57 offset:256
	ds_read_b128 v[214:217], v58 offset:256
	ds_read_b128 v[218:221], v59 offset:256
	ds_read_b128 v[222:225], v60 offset:256
	s_waitcnt vmcnt(30) lgkmcnt(7)
	v_mfma_f32_16x16x32_bf16 v[2:5], v[194:197], v[66:69], v[2:5]
	v_mfma_f32_16x16x32_bf16 v[6:9], v[194:197], v[70:73], v[6:9]
	global_load_dwordx4 v[66:69], v[62:63], off offset:1024
	global_load_dwordx4 v[70:73], v[64:65], off offset:1024
	ds_read_b128 v[194:197], v57 offset:512
	s_waitcnt vmcnt(30) lgkmcnt(7)
	v_mfma_f32_16x16x32_bf16 v[2:5], v[198:201], v[74:77], v[2:5]
	v_mfma_f32_16x16x32_bf16 v[6:9], v[198:201], v[78:81], v[6:9]
	global_load_dwordx4 v[74:77], v[62:63], off offset:1088
	global_load_dwordx4 v[78:81], v[64:65], off offset:1088
	ds_read_b128 v[198:201], v58 offset:512
	s_waitcnt vmcnt(30) lgkmcnt(7)
	v_mfma_f32_16x16x32_bf16 v[2:5], v[202:205], v[82:85], v[2:5]
	v_mfma_f32_16x16x32_bf16 v[6:9], v[202:205], v[86:89], v[6:9]
	global_load_dwordx4 v[82:85], v[62:63], off offset:1152
	global_load_dwordx4 v[86:89], v[64:65], off offset:1152
	ds_read_b128 v[202:205], v59 offset:512
	s_waitcnt vmcnt(30) lgkmcnt(7)
	v_mfma_f32_16x16x32_bf16 v[2:5], v[206:209], v[90:93], v[2:5]
	v_mfma_f32_16x16x32_bf16 v[6:9], v[206:209], v[94:97], v[6:9]
	global_load_dwordx4 v[90:93], v[62:63], off offset:1216
	global_load_dwordx4 v[94:97], v[64:65], off offset:1216
	ds_read_b128 v[206:209], v60 offset:512
	s_waitcnt vmcnt(30) lgkmcnt(7)
	v_mfma_f32_16x16x32_bf16 v[2:5], v[210:213], v[98:101], v[2:5]
	v_mfma_f32_16x16x32_bf16 v[6:9], v[210:213], v[102:105], v[6:9]
	global_load_dwordx4 v[98:101], v[62:63], off offset:1280
	global_load_dwordx4 v[102:105], v[64:65], off offset:1280
	ds_read_b128 v[210:213], v57 offset:768
	s_waitcnt vmcnt(30) lgkmcnt(7)
	v_mfma_f32_16x16x32_bf16 v[2:5], v[214:217], v[106:109], v[2:5]
	v_mfma_f32_16x16x32_bf16 v[6:9], v[214:217], v[110:113], v[6:9]
	global_load_dwordx4 v[106:109], v[62:63], off offset:1344
	global_load_dwordx4 v[110:113], v[64:65], off offset:1344
	ds_read_b128 v[214:217], v58 offset:768
	s_waitcnt vmcnt(30) lgkmcnt(7)
	v_mfma_f32_16x16x32_bf16 v[2:5], v[218:221], v[114:117], v[2:5]
	v_mfma_f32_16x16x32_bf16 v[6:9], v[218:221], v[118:121], v[6:9]
	global_load_dwordx4 v[114:117], v[62:63], off offset:1408
	global_load_dwordx4 v[118:121], v[64:65], off offset:1408
	ds_read_b128 v[218:221], v59 offset:768
	s_waitcnt vmcnt(30) lgkmcnt(7)
	v_mfma_f32_16x16x32_bf16 v[2:5], v[222:225], v[122:125], v[2:5]
	v_mfma_f32_16x16x32_bf16 v[6:9], v[222:225], v[126:129], v[6:9]
	global_load_dwordx4 v[122:125], v[62:63], off offset:1472
	global_load_dwordx4 v[126:129], v[64:65], off offset:1472
	ds_read_b128 v[222:225], v60 offset:768
	s_waitcnt vmcnt(30) lgkmcnt(7)
	v_mfma_f32_16x16x32_bf16 v[2:5], v[194:197], v[130:133], v[2:5]
	v_mfma_f32_16x16x32_bf16 v[6:9], v[194:197], v[134:137], v[6:9]
	global_load_dwordx4 v[130:133], v[62:63], off offset:1536
	global_load_dwordx4 v[134:137], v[64:65], off offset:1536
	ds_read_b128 v[194:197], v57 offset:1024
	s_waitcnt vmcnt(30) lgkmcnt(7)
; #define LAS __attribute__((address_space(3)))
; template <int MODE>
; __device__ __forceinline__ void ctx_small_gemm(PREF P, unsigned char* shm) {
;     ...
; #pragma unroll 4
;             for (int ks = 0; ks < KS; ++ks) {
;                 const bf16x8 a0 = *(const LAS bf16x8*)(lds + (rt0 * 16 + r) * (K * 2) + (((ks * 4 + q) ^ r) << 4));
;                 const bf16x8 b0 = *(const bf16x8*)(W0 + ks * 32);
;                 if (MODE == 0) { const bf16x8 b1 = *(const bf16x8*)(W1 + ks * 32);
;                     acc0 = __builtin_amdgcn_mfma_f32_16x16x32_bf16(a0, b0, acc0, 0, 0, 0); acc1 = __builtin_amdgcn_mfma_f32_16x16x32_bf16(a0, b1, acc1, 0, 0, 0); }
	v_mfma_f32_16x16x32_bf16 v[2:5], v[198:201], v[138:141], v[2:5]
	v_mfma_f32_16x16x32_bf16 v[6:9], v[198:201], v[142:145], v[6:9]
	global_load_dwordx4 v[138:141], v[62:63], off offset:1600
	global_load_dwordx4 v[142:145], v[64:65], off offset:1600
	ds_read_b128 v[198:201], v58 offset:1024
	s_waitcnt vmcnt(30) lgkmcnt(7)
	v_mfma_f32_16x16x32_bf16 v[2:5], v[202:205], v[146:149], v[2:5]
	v_mfma_f32_16x16x32_bf16 v[6:9], v[202:205], v[150:153], v[6:9]
	global_load_dwordx4 v[146:149], v[62:63], off offset:1664
	global_load_dwordx4 v[150:153], v[64:65], off offset:1664
	ds_read_b128 v[202:205], v59 offset:1024
	s_waitcnt vmcnt(30) lgkmcnt(7)
	v_mfma_f32_16x16x32_bf16 v[2:5], v[206:209], v[154:157], v[2:5]
	v_mfma_f32_16x16x32_bf16 v[6:9], v[206:209], v[158:161], v[6:9]
	global_load_dwordx4 v[154:157], v[62:63], off offset:1728
	global_load_dwordx4 v[158:161], v[64:65], off offset:1728
	ds_read_b128 v[206:209], v60 offset:1024
	s_waitcnt vmcnt(30) lgkmcnt(7)
	v_mfma_f32_16x16x32_bf16 v[2:5], v[210:213], v[162:165], v[2:5]
	v_mfma_f32_16x16x32_bf16 v[6:9], v[210:213], v[166:169], v[6:9]
	global_load_dwordx4 v[162:165], v[62:63], off offset:1792
	global_load_dwordx4 v[166:169], v[64:65], off offset:1792
	ds_read_b128 v[210:213], v57 offset:1280
	s_waitcnt vmcnt(30) lgkmcnt(7)
	v_mfma_f32_16x16x32_bf16 v[2:5], v[214:217], v[170:173], v[2:5]
	v_mfma_f32_16x16x32_bf16 v[6:9], v[214:217], v[174:177], v[6:9]
	global_load_dwordx4 v[170:173], v[62:63], off offset:1856
	global_load_dwordx4 v[174:177], v[64:65], off offset:1856
	ds_read_b128 v[214:217], v58 offset:1280
	s_waitcnt vmcnt(30) lgkmcnt(7)
	v_mfma_f32_16x16x32_bf16 v[2:5], v[218:221], v[178:181], v[2:5]
	v_mfma_f32_16x16x32_bf16 v[6:9], v[218:221], v[182:185], v[6:9]
	global_load_dwordx4 v[178:181], v[62:63], off offset:1920
	global_load_dwordx4 v[182:185], v[64:65], off offset:1920
	ds_read_b128 v[218:221], v59 offset:1280
	s_waitcnt vmcnt(30) lgkmcnt(7)
	v_mfma_f32_16x16x32_bf16 v[2:5], v[222:225], v[186:189], v[2:5]
	v_mfma_f32_16x16x32_bf16 v[6:9], v[222:225], v[190:193], v[6:9]
	global_load_dwordx4 v[186:189], v[62:63], off offset:1984
	global_load_dwordx4 v[190:193], v[64:65], off offset:1984
	ds_read_b128 v[222:225], v60 offset:1280
	s_waitcnt vmcnt(30) lgkmcnt(7)
	v_mfma_f32_16x16x32_bf16 v[2:5], v[194:197], v[66:69], v[2:5]
	v_mfma_f32_16x16x32_bf16 v[6:9], v[194:197], v[70:73], v[6:9]
	ds_read_b128 v[194:197], v57 offset:1536
	s_waitcnt vmcnt(28) lgkmcnt(7)
	v_mfma_f32_16x16x32_bf16 v[2:5], v[198:201], v[74:77], v[2:5]
	v_mfma_f32_16x16x32_bf16 v[6:9], v[198:201], v[78:81], v[6:9]
	ds_read_b128 v[198:201], v58 offset:1536
	s_waitcnt vmcnt(26) lgkmcnt(7)
	v_mfma_f32_16x16x32_bf16 v[2:5], v[202:205], v[82:85], v[2:5]
	v_mfma_f32_16x16x32_bf16 v[6:9], v[202:205], v[86:89], v[6:9]
	ds_read_b128 v[202:205], v59 offset:1536
	s_waitcnt vmcnt(24) lgkmcnt(7)
	v_mfma_f32_16x16x32_bf16 v[2:5], v[206:209], v[90:93], v[2:5]
	v_mfma_f32_16x16x32_bf16 v[6:9], v[206:209], v[94:97], v[6:9]
	ds_read_b128 v[206:209], v60 offset:1536
	s_waitcnt vmcnt(22) lgkmcnt(7)
	v_mfma_f32_16x16x32_bf16 v[2:5], v[210:213], v[98:101], v[2:5]
	v_mfma_f32_16x16x32_bf16 v[6:9], v[210:213], v[102:105], v[6:9]
	ds_read_b128 v[210:213], v57 offset:1792
	s_waitcnt vmcnt(20) lgkmcnt(7)
	v_mfma_f32_16x16x32_bf16 v[2:5], v[214:217], v[106:109], v[2:5]
	v_mfma_f32_16x16x32_bf16 v[6:9], v[214:217], v[110:113], v[6:9]
	ds_read_b128 v[214:217], v58 offset:1792
	s_waitcnt vmcnt(18) lgkmcnt(7)
	v_mfma_f32_16x16x32_bf16 v[2:5], v[218:221], v[114:117], v[2:5]
	v_mfma_f32_16x16x32_bf16 v[6:9], v[218:221], v[118:121], v[6:9]
	ds_read_b128 v[218:221], v59 offset:1792
	s_waitcnt vmcnt(16) lgkmcnt(7)
	v_mfma_f32_16x16x32_bf16 v[2:5], v[222:225], v[122:125], v[2:5]
	v_mfma_f32_16x16x32_bf16 v[6:9], v[222:225], v[126:129], v[6:9]
	ds_read_b128 v[222:225], v60 offset:1792
	s_waitcnt vmcnt(14) lgkmcnt(7)
	v_mfma_f32_16x16x32_bf16 v[2:5], v[194:197], v[130:133], v[2:5]
	v_mfma_f32_16x16x32_bf16 v[6:9], v[194:197], v[134:137], v[6:9]
	s_waitcnt vmcnt(12) lgkmcnt(6)
; #define LAS __attribute__((address_space(3)))
; __device__ __forceinline__ float bf2f(unsigned v) { return __uint_as_float(v << 16); }
; __device__ __forceinline__ unsigned cvt_pk_bf16(float lo, float hi) { unsigned r; asm volatile("v_cvt_pk_bf16_f32 %0, %1, %2" : "=v"(r) : "v"(lo), "v"(hi)); return r; }
; __device__ __forceinline__ float sigmoidf_(float x) { return __builtin_amdgcn_rcpf(1.0f + __expf(-x)); }
; __device__ __forceinline__ float siluf_(float x) { return x * __builtin_amdgcn_rcpf(1.0f + __expf(-x)); }
; template <int MODE>
; __device__ __forceinline__ void ctx_small_gemm(PREF P, unsigned char* shm) {
;     ...
; #pragma unroll 4
;             for (int ks = 0; ks < KS; ++ks) {
;                 const bf16x8 a0 = *(const LAS bf16x8*)(lds + (rt0 * 16 + r) * (K * 2) + (((ks * 4 + q) ^ r) << 4));
;                 const bf16x8 b0 = *(const bf16x8*)(W0 + ks * 32);
;                 if (MODE == 0) { const bf16x8 b1 = *(const bf16x8*)(W1 + ks * 32);
;                     acc0 = __builtin_amdgcn_mfma_f32_16x16x32_bf16(a0, b0, acc0, 0, 0, 0); acc1 = __builtin_amdgcn_mfma_f32_16x16x32_bf16(a0, b1, acc1, 0, 0, 0); }
;     ...
;             if (MODE == 0) { bf16_t* BBo = (bf16_t*)(P.ws + O_BB); float zq[4];
; #pragma unroll
;                 for (int i = 0; i < 4; ++i) { const int row = row_base + rt0 * 16 + q * 4 + i; zq[i] = bf2f(parts[E_PZB + (size_t)row * 1024 + col]); }
; #pragma unroll
;                 for (int i = 0; i < 4; ++i) { const int row = row_base + rt0 * 16 + q * 4 + i; const float z = zq[i];
;                     BBo[(size_t)row * 1024 + col] = (bf16_t)(cvt_pk_bf16(acc0[i] * sigmoidf_(acc1[i]) * siluf_(z), 0.f) & 0xffffu); }
	v_mfma_f32_16x16x32_bf16 v[2:5], v[198:201], v[138:141], v[2:5]
	v_mfma_f32_16x16x32_bf16 v[6:9], v[198:201], v[142:145], v[6:9]
	s_waitcnt vmcnt(10) lgkmcnt(5)
	v_mfma_f32_16x16x32_bf16 v[2:5], v[202:205], v[146:149], v[2:5]
	v_mfma_f32_16x16x32_bf16 v[6:9], v[202:205], v[150:153], v[6:9]
	s_waitcnt vmcnt(8) lgkmcnt(4)
	v_mfma_f32_16x16x32_bf16 v[2:5], v[206:209], v[154:157], v[2:5]
	v_mfma_f32_16x16x32_bf16 v[6:9], v[206:209], v[158:161], v[6:9]
	s_waitcnt vmcnt(6) lgkmcnt(3)
	v_mfma_f32_16x16x32_bf16 v[2:5], v[210:213], v[162:165], v[2:5]
	v_mfma_f32_16x16x32_bf16 v[6:9], v[210:213], v[166:169], v[6:9]
	s_waitcnt vmcnt(4) lgkmcnt(2)
	v_mfma_f32_16x16x32_bf16 v[2:5], v[214:217], v[170:173], v[2:5]
	v_mfma_f32_16x16x32_bf16 v[6:9], v[214:217], v[174:177], v[6:9]
	s_waitcnt vmcnt(2) lgkmcnt(1)
	v_mfma_f32_16x16x32_bf16 v[2:5], v[218:221], v[178:181], v[2:5]
	v_mfma_f32_16x16x32_bf16 v[6:9], v[218:221], v[182:185], v[6:9]
	s_waitcnt vmcnt(0) lgkmcnt(0)
	v_mfma_f32_16x16x32_bf16 v[2:5], v[222:225], v[186:189], v[2:5]
	v_mfma_f32_16x16x32_bf16 v[6:9], v[222:225], v[190:193], v[6:9]
	s_mov_b64 s[16:17], 0x800
	v_add_u32_e32 v10, 0x80, v10
	s_cmpk_eq_i32 s16, 0x800
	s_lshl_b32 s16, s0, 5
	s_and_b32 s16, s16, 0x3e0
	v_add_u32_e32 v14, s20, v20
	v_or_b32_e32 v10, s16, v18
	v_ashrrev_i32_e32 v15, 31, v14
	v_lshlrev_b32_e32 v10, 1, v10
	v_lshlrev_b64 v[26:27], 11, v[14:15]
	v_or_b32_e32 v30, 1, v14
	v_or_b32_e32 v34, 2, v14
	v_or_b32_e32 v14, 3, v14
	v_lshl_add_u64 v[24:25], s[14:15], 0, v[10:11]
	v_ashrrev_i32_e32 v31, 31, v30
	v_ashrrev_i32_e32 v35, 31, v34
	v_ashrrev_i32_e32 v15, 31, v14
	v_lshl_add_u64 v[28:29], v[24:25], 0, v[26:27]
	v_lshlrev_b64 v[30:31], 11, v[30:31]
	v_lshlrev_b64 v[34:35], 11, v[34:35]
	v_lshlrev_b64 v[14:15], 11, v[14:15]
	v_lshl_add_u64 v[32:33], v[24:25], 0, v[30:31]
	v_lshl_add_u64 v[36:37], v[24:25], 0, v[34:35]
	v_lshl_add_u64 v[24:25], v[24:25], 0, v[14:15]
	global_load_ushort v23, v[28:29], off
	global_load_ushort v38, v[32:33], off
	global_load_ushort v39, v[36:37], off
	global_load_ushort v40, v[24:25], off
	v_mul_f32_e32 v6, 0xbfb8aa3b, v6
	v_mul_f32_e32 v8, 0xbfb8aa3b, v8
	v_mul_f32_e32 v9, 0xbfb8aa3b, v9
	v_exp_f32_e32 v24, v6
	v_mul_f32_e32 v7, 0xbfb8aa3b, v7
	v_exp_f32_e32 v28, v8
	v_exp_f32_e32 v29, v9
	v_exp_f32_e32 v25, v7
	v_lshl_add_u64 v[6:7], s[12:13], 0, v[10:11]
	v_add_f32_e32 v10, 1.0, v24
	v_add_f32_e32 v28, 1.0, v28
	v_add_f32_e32 v29, 1.0, v29
	v_rcp_f32_e32 v10, v10
	v_lshl_add_u64 v[8:9], v[6:7], 0, v[26:27]
	v_add_f32_e32 v32, 1.0, v25
	v_lshl_add_u64 v[24:25], v[6:7], 0, v[30:31]
	v_lshl_add_u64 v[26:27], v[6:7], 0, v[34:35]
	v_lshl_add_u64 v[6:7], v[6:7], 0, v[14:15]
	v_rcp_f32_e32 v15, v28
	v_rcp_f32_e32 v28, v29
	v_rcp_f32_e32 v14, v32
	v_mul_f32_e32 v2, v2, v10
	v_mul_f32_e32 v4, v4, v15
	v_mul_f32_e32 v5, v5, v28
	v_mul_f32_e32 v3, v3, v14
	s_add_i32 s0, s0, s33
	s_add_i32 s1, s1, s2
	s_cmpk_gt_i32 s0, 0xff
	s_waitcnt vmcnt(3)
	v_lshlrev_b32_e32 v10, 16, v23
	v_mul_f32_e32 v28, 0xbfb8aa3b, v10
	s_waitcnt vmcnt(2)
	v_lshlrev_b32_e32 v14, 16, v38
	v_exp_f32_e32 v28, v28
	s_waitcnt vmcnt(1)
	v_lshlrev_b32_e32 v15, 16, v39
	v_mul_f32_e32 v29, 0xbfb8aa3b, v14
	s_waitcnt vmcnt(0)
	v_lshlrev_b32_e32 v23, 16, v40
	v_mul_f32_e32 v30, 0xbfb8aa3b, v15
	v_exp_f32_e32 v29, v29
	v_mul_f32_e32 v31, 0xbfb8aa3b, v23
	v_exp_f32_e32 v30, v30
	v_exp_f32_e32 v31, v31
	v_add_f32_e32 v28, 1.0, v28
	v_rcp_f32_e32 v28, v28
	v_add_f32_e32 v29, 1.0, v29
	v_add_f32_e32 v30, 1.0, v30
	v_rcp_f32_e32 v29, v29
	v_add_f32_e32 v31, 1.0, v31
	v_rcp_f32_e32 v30, v30
	v_rcp_f32_e32 v31, v31
	v_mul_f32_e32 v10, v28, v10
	v_mul_f32_e32 v2, v2, v10
	v_mul_f32_e32 v14, v29, v14
	v_cvt_pk_bf16_f32 v2, v2, v11
	v_mul_f32_e32 v15, v30, v15
	v_mul_f32_e32 v3, v3, v14
	global_store_short v[8:9], v2, off
	v_cvt_pk_bf16_f32 v2, v3, v11
	v_mul_f32_e32 v23, v31, v23
	v_mul_f32_e32 v4, v4, v15
	global_store_short v[24:25], v2, off
	v_cvt_pk_bf16_f32 v2, v4, v11
	v_mul_f32_e32 v5, v5, v23
	global_store_short v[26:27], v2, off
	v_cvt_pk_bf16_f32 v2, v5, v11
	global_store_short v[6:7], v2, off
	s_barrier
	s_cbranch_scc0 .LBB0_714

; #define LAS __attribute__((address_space(3)))
; template <int MODE>
; __device__ __forceinline__ void ctx_small_gemm(PREF P, unsigned char* shm) {
;     ...
; #pragma unroll 4
;             for (int ks = 0; ks < KS; ++ks) {
;                 const bf16x8 a0 = *(const LAS bf16x8*)(lds + (rt0 * 16 + r) * (K * 2) + (((ks * 4 + q) ^ r) << 4));
;                 const bf16x8 b0 = *(const bf16x8*)(W0 + ks * 32);
;                 if (MODE == 0) { const bf16x8 b1 = *(const bf16x8*)(W1 + ks * 32);
;                     acc0 = __builtin_amdgcn_mfma_f32_16x16x32_bf16(a0, b0, acc0, 0, 0, 0); acc1 = __builtin_amdgcn_mfma_f32_16x16x32_bf16(a0, b1, acc1, 0, 0, 0); }
;                 else if (MODE == 3) { acc0 = __builtin_amdgcn_mfma_f32_16x16x32_bf16(a0, b0, acc0, 0, 0, 0); }
.LBB0_726:
	v_xor_b32_e32 v43, v13, v12
	v_lshl_add_u32 v44, v43, 4, v14
	v_add_u32_e32 v43, 4, v13
	v_xor_b32_e32 v43, v43, v12
	v_lshl_add_u32 v45, v43, 4, v14
	v_add_u32_e32 v43, 8, v13
	v_xor_b32_e32 v43, v43, v12
	v_lshl_add_u32 v46, v43, 4, v14
	v_add_u32_e32 v43, 12, v13
	v_xor_b32_e32 v43, v43, v12
	v_lshl_add_u32 v47, v43, 4, v14
	global_load_dwordx4 v[48:51], v[10:11], off offset:-192
	global_load_dwordx4 v[52:55], v[10:11], off offset:-128
	global_load_dwordx4 v[56:59], v[10:11], off offset:-64
	global_load_dwordx4 v[60:63], v[10:11], off
	global_load_dwordx4 v[64:67], v[10:11], off offset:64
	global_load_dwordx4 v[68:71], v[10:11], off offset:128
	global_load_dwordx4 v[72:75], v[10:11], off offset:192
	global_load_dwordx4 v[76:79], v[10:11], off offset:256
	global_load_dwordx4 v[80:83], v[10:11], off offset:320
	global_load_dwordx4 v[84:87], v[10:11], off offset:384
	global_load_dwordx4 v[88:91], v[10:11], off offset:448
	global_load_dwordx4 v[92:95], v[10:11], off offset:512
	global_load_dwordx4 v[96:99], v[10:11], off offset:576
	global_load_dwordx4 v[100:103], v[10:11], off offset:640
	global_load_dwordx4 v[104:107], v[10:11], off offset:704
	global_load_dwordx4 v[108:111], v[10:11], off offset:768
	global_load_dwordx4 v[112:115], v[10:11], off offset:832
	global_load_dwordx4 v[116:119], v[10:11], off offset:896
	global_load_dwordx4 v[120:123], v[10:11], off offset:960
	global_load_dwordx4 v[124:127], v[10:11], off offset:1024
	global_load_dwordx4 v[128:131], v[10:11], off offset:1088
	global_load_dwordx4 v[132:135], v[10:11], off offset:1152
	global_load_dwordx4 v[136:139], v[10:11], off offset:1216
	global_load_dwordx4 v[140:143], v[10:11], off offset:1280
	global_load_dwordx4 v[144:147], v[10:11], off offset:1344
	global_load_dwordx4 v[148:151], v[10:11], off offset:1408
	global_load_dwordx4 v[152:155], v[10:11], off offset:1472
	global_load_dwordx4 v[156:159], v[10:11], off offset:1536
	global_load_dwordx4 v[160:163], v[10:11], off offset:1600
	global_load_dwordx4 v[164:167], v[10:11], off offset:1664
	global_load_dwordx4 v[168:171], v[10:11], off offset:1728
	global_load_dwordx4 v[172:175], v[10:11], off offset:1792
	ds_read_b128 v[176:179], v44
	ds_read_b128 v[180:183], v45
	ds_read_b128 v[184:187], v46
	ds_read_b128 v[188:191], v47
	ds_read_b128 v[192:195], v44 offset:256
	ds_read_b128 v[196:199], v45 offset:256
	ds_read_b128 v[200:203], v46 offset:256
	ds_read_b128 v[204:207], v47 offset:256
	s_waitcnt vmcnt(31) lgkmcnt(7)
	v_mfma_f32_16x16x32_bf16 v[2:5], v[176:179], v[48:51], v[2:5]
	global_load_dwordx4 v[48:51], v[10:11], off offset:1856
	ds_read_b128 v[176:179], v44 offset:512
	s_waitcnt vmcnt(31) lgkmcnt(7)
	v_mfma_f32_16x16x32_bf16 v[2:5], v[180:183], v[52:55], v[2:5]
	global_load_dwordx4 v[52:55], v[10:11], off offset:1920
	ds_read_b128 v[180:183], v45 offset:512
	s_waitcnt vmcnt(31) lgkmcnt(7)
	v_mfma_f32_16x16x32_bf16 v[2:5], v[184:187], v[56:59], v[2:5]
	global_load_dwordx4 v[56:59], v[10:11], off offset:1984
	ds_read_b128 v[184:187], v46 offset:512
	s_waitcnt vmcnt(31) lgkmcnt(7)
	v_mfma_f32_16x16x32_bf16 v[2:5], v[188:191], v[60:63], v[2:5]
	global_load_dwordx4 v[60:63], v[10:11], off offset:2048
	ds_read_b128 v[188:191], v47 offset:512
	s_waitcnt vmcnt(31) lgkmcnt(7)
	v_mfma_f32_16x16x32_bf16 v[2:5], v[192:195], v[64:67], v[2:5]
	global_load_dwordx4 v[64:67], v[10:11], off offset:2112
	ds_read_b128 v[192:195], v44 offset:768
	s_waitcnt vmcnt(31) lgkmcnt(7)
	v_mfma_f32_16x16x32_bf16 v[2:5], v[196:199], v[68:71], v[2:5]
	global_load_dwordx4 v[68:71], v[10:11], off offset:2176
	ds_read_b128 v[196:199], v45 offset:768
	s_waitcnt vmcnt(31) lgkmcnt(7)
	v_mfma_f32_16x16x32_bf16 v[2:5], v[200:203], v[72:75], v[2:5]
	global_load_dwordx4 v[72:75], v[10:11], off offset:2240
	ds_read_b128 v[200:203], v46 offset:768
	s_waitcnt vmcnt(31) lgkmcnt(7)
	v_mfma_f32_16x16x32_bf16 v[2:5], v[204:207], v[76:79], v[2:5]
	global_load_dwordx4 v[76:79], v[10:11], off offset:2304
	ds_read_b128 v[204:207], v47 offset:768
	s_waitcnt vmcnt(31) lgkmcnt(7)
	v_mfma_f32_16x16x32_bf16 v[2:5], v[176:179], v[80:83], v[2:5]
	global_load_dwordx4 v[80:83], v[10:11], off offset:2368
	ds_read_b128 v[176:179], v44 offset:1024
	s_waitcnt vmcnt(31) lgkmcnt(7)
	v_mfma_f32_16x16x32_bf16 v[2:5], v[180:183], v[84:87], v[2:5]
	global_load_dwordx4 v[84:87], v[10:11], off offset:2432
	ds_read_b128 v[180:183], v45 offset:1024
	s_waitcnt vmcnt(31) lgkmcnt(7)
	v_mfma_f32_16x16x32_bf16 v[2:5], v[184:187], v[88:91], v[2:5]
	global_load_dwordx4 v[88:91], v[10:11], off offset:2496
	ds_read_b128 v[184:187], v46 offset:1024
	s_waitcnt vmcnt(31) lgkmcnt(7)
	v_mfma_f32_16x16x32_bf16 v[2:5], v[188:191], v[92:95], v[2:5]
	global_load_dwordx4 v[92:95], v[10:11], off offset:2560
	ds_read_b128 v[188:191], v47 offset:1024
	s_waitcnt vmcnt(31) lgkmcnt(7)
	v_mfma_f32_16x16x32_bf16 v[2:5], v[192:195], v[96:99], v[2:5]
	global_load_dwordx4 v[96:99], v[10:11], off offset:2624
	ds_read_b128 v[192:195], v44 offset:1280
	s_waitcnt vmcnt(31) lgkmcnt(7)
	v_mfma_f32_16x16x32_bf16 v[2:5], v[196:199], v[100:103], v[2:5]
	global_load_dwordx4 v[100:103], v[10:11], off offset:2688
	ds_read_b128 v[196:199], v45 offset:1280
	s_waitcnt vmcnt(31) lgkmcnt(7)
	v_mfma_f32_16x16x32_bf16 v[2:5], v[200:203], v[104:107], v[2:5]
	global_load_dwordx4 v[104:107], v[10:11], off offset:2752
	ds_read_b128 v[200:203], v46 offset:1280
	s_waitcnt vmcnt(31) lgkmcnt(7)
	v_mfma_f32_16x16x32_bf16 v[2:5], v[204:207], v[108:111], v[2:5]
	global_load_dwordx4 v[108:111], v[10:11], off offset:2816
	ds_read_b128 v[204:207], v47 offset:1280
	s_waitcnt vmcnt(31) lgkmcnt(7)
; #define LAS __attribute__((address_space(3)))
; template <int MODE>
; __device__ __forceinline__ void ctx_small_gemm(PREF P, unsigned char* shm) {
;     ...
; #pragma unroll 4
;             for (int ks = 0; ks < KS; ++ks) {
;                 const bf16x8 a0 = *(const LAS bf16x8*)(lds + (rt0 * 16 + r) * (K * 2) + (((ks * 4 + q) ^ r) << 4));
;                 const bf16x8 b0 = *(const bf16x8*)(W0 + ks * 32);
;                 if (MODE == 0) { const bf16x8 b1 = *(const bf16x8*)(W1 + ks * 32);
;                     acc0 = __builtin_amdgcn_mfma_f32_16x16x32_bf16(a0, b0, acc0, 0, 0, 0); acc1 = __builtin_amdgcn_mfma_f32_16x16x32_bf16(a0, b1, acc1, 0, 0, 0); }
;                 else if (MODE == 3) { acc0 = __builtin_amdgcn_mfma_f32_16x16x32_bf16(a0, b0, acc0, 0, 0, 0); }
	v_mfma_f32_16x16x32_bf16 v[2:5], v[176:179], v[112:115], v[2:5]
	global_load_dwordx4 v[112:115], v[10:11], off offset:2880
	ds_read_b128 v[176:179], v44 offset:1536
	s_waitcnt vmcnt(31) lgkmcnt(7)
	v_mfma_f32_16x16x32_bf16 v[2:5], v[180:183], v[116:119], v[2:5]
	global_load_dwordx4 v[116:119], v[10:11], off offset:2944
	ds_read_b128 v[180:183], v45 offset:1536
	s_waitcnt vmcnt(31) lgkmcnt(7)
	v_mfma_f32_16x16x32_bf16 v[2:5], v[184:187], v[120:123], v[2:5]
	global_load_dwordx4 v[120:123], v[10:11], off offset:3008
	ds_read_b128 v[184:187], v46 offset:1536
	s_waitcnt vmcnt(31) lgkmcnt(7)
	v_mfma_f32_16x16x32_bf16 v[2:5], v[188:191], v[124:127], v[2:5]
	global_load_dwordx4 v[124:127], v[10:11], off offset:3072
	ds_read_b128 v[188:191], v47 offset:1536
	s_waitcnt vmcnt(31) lgkmcnt(7)
	v_mfma_f32_16x16x32_bf16 v[2:5], v[192:195], v[128:131], v[2:5]
	global_load_dwordx4 v[128:131], v[10:11], off offset:3136
	ds_read_b128 v[192:195], v44 offset:1792
	s_waitcnt vmcnt(31) lgkmcnt(7)
	v_mfma_f32_16x16x32_bf16 v[2:5], v[196:199], v[132:135], v[2:5]
	global_load_dwordx4 v[132:135], v[10:11], off offset:3200
	ds_read_b128 v[196:199], v45 offset:1792
	s_waitcnt vmcnt(31) lgkmcnt(7)
	v_mfma_f32_16x16x32_bf16 v[2:5], v[200:203], v[136:139], v[2:5]
	global_load_dwordx4 v[136:139], v[10:11], off offset:3264
	ds_read_b128 v[200:203], v46 offset:1792
	s_waitcnt vmcnt(31) lgkmcnt(7)
	v_mfma_f32_16x16x32_bf16 v[2:5], v[204:207], v[140:143], v[2:5]
	global_load_dwordx4 v[140:143], v[10:11], off offset:3328
	ds_read_b128 v[204:207], v47 offset:1792
	s_waitcnt vmcnt(31) lgkmcnt(7)
	v_mfma_f32_16x16x32_bf16 v[2:5], v[176:179], v[144:147], v[2:5]
	global_load_dwordx4 v[144:147], v[10:11], off offset:3392
	ds_read_b128 v[176:179], v44 offset:2048
	s_waitcnt vmcnt(31) lgkmcnt(7)
	v_mfma_f32_16x16x32_bf16 v[2:5], v[180:183], v[148:151], v[2:5]
	global_load_dwordx4 v[148:151], v[10:11], off offset:3456
	ds_read_b128 v[180:183], v45 offset:2048
	s_waitcnt vmcnt(31) lgkmcnt(7)
	v_mfma_f32_16x16x32_bf16 v[2:5], v[184:187], v[152:155], v[2:5]
	global_load_dwordx4 v[152:155], v[10:11], off offset:3520
	ds_read_b128 v[184:187], v46 offset:2048
	s_waitcnt vmcnt(31) lgkmcnt(7)
	v_mfma_f32_16x16x32_bf16 v[2:5], v[188:191], v[156:159], v[2:5]
	global_load_dwordx4 v[156:159], v[10:11], off offset:3584
	ds_read_b128 v[188:191], v47 offset:2048
	s_waitcnt vmcnt(31) lgkmcnt(7)
	v_mfma_f32_16x16x32_bf16 v[2:5], v[192:195], v[160:163], v[2:5]
	global_load_dwordx4 v[160:163], v[10:11], off offset:3648
	ds_read_b128 v[192:195], v44 offset:2304
	s_waitcnt vmcnt(31) lgkmcnt(7)
	v_mfma_f32_16x16x32_bf16 v[2:5], v[196:199], v[164:167], v[2:5]
	global_load_dwordx4 v[164:167], v[10:11], off offset:3712
	ds_read_b128 v[196:199], v45 offset:2304
	s_waitcnt vmcnt(31) lgkmcnt(7)
	v_mfma_f32_16x16x32_bf16 v[2:5], v[200:203], v[168:171], v[2:5]
	global_load_dwordx4 v[168:171], v[10:11], off offset:3776
	ds_read_b128 v[200:203], v46 offset:2304
	s_waitcnt vmcnt(31) lgkmcnt(7)
	v_mfma_f32_16x16x32_bf16 v[2:5], v[204:207], v[172:175], v[2:5]
	global_load_dwordx4 v[172:175], v[10:11], off offset:3840
	ds_read_b128 v[204:207], v47 offset:2304
	s_waitcnt vmcnt(31) lgkmcnt(7)
	v_mfma_f32_16x16x32_bf16 v[2:5], v[176:179], v[48:51], v[2:5]
	ds_read_b128 v[176:179], v44 offset:2560
	s_waitcnt vmcnt(30) lgkmcnt(7)
	v_mfma_f32_16x16x32_bf16 v[2:5], v[180:183], v[52:55], v[2:5]
	ds_read_b128 v[180:183], v45 offset:2560
	s_waitcnt vmcnt(29) lgkmcnt(7)
	v_mfma_f32_16x16x32_bf16 v[2:5], v[184:187], v[56:59], v[2:5]
	ds_read_b128 v[184:187], v46 offset:2560
	s_waitcnt vmcnt(28) lgkmcnt(7)
	v_mfma_f32_16x16x32_bf16 v[2:5], v[188:191], v[60:63], v[2:5]
	ds_read_b128 v[188:191], v47 offset:2560
	s_waitcnt vmcnt(27) lgkmcnt(7)
	v_mfma_f32_16x16x32_bf16 v[2:5], v[192:195], v[64:67], v[2:5]
	ds_read_b128 v[192:195], v44 offset:2816
	s_waitcnt vmcnt(26) lgkmcnt(7)
	v_mfma_f32_16x16x32_bf16 v[2:5], v[196:199], v[68:71], v[2:5]
	ds_read_b128 v[196:199], v45 offset:2816
	s_waitcnt vmcnt(25) lgkmcnt(7)
	v_mfma_f32_16x16x32_bf16 v[2:5], v[200:203], v[72:75], v[2:5]
	ds_read_b128 v[200:203], v46 offset:2816
	s_waitcnt vmcnt(24) lgkmcnt(7)
	v_mfma_f32_16x16x32_bf16 v[2:5], v[204:207], v[76:79], v[2:5]
	ds_read_b128 v[204:207], v47 offset:2816
	s_waitcnt vmcnt(23) lgkmcnt(7)
	v_mfma_f32_16x16x32_bf16 v[2:5], v[176:179], v[80:83], v[2:5]
	ds_read_b128 v[176:179], v44 offset:3072
	s_waitcnt vmcnt(22) lgkmcnt(7)
	v_mfma_f32_16x16x32_bf16 v[2:5], v[180:183], v[84:87], v[2:5]
	ds_read_b128 v[180:183], v45 offset:3072
	s_waitcnt vmcnt(21) lgkmcnt(7)
	v_mfma_f32_16x16x32_bf16 v[2:5], v[184:187], v[88:91], v[2:5]
	ds_read_b128 v[184:187], v46 offset:3072
	s_waitcnt vmcnt(20) lgkmcnt(7)
	v_mfma_f32_16x16x32_bf16 v[2:5], v[188:191], v[92:95], v[2:5]
	ds_read_b128 v[188:191], v47 offset:3072
	s_waitcnt vmcnt(19) lgkmcnt(7)
; #define LAS __attribute__((address_space(3)))
; __device__ __forceinline__ float bf2f(unsigned v) { return __uint_as_float(v << 16); }
; __device__ __forceinline__ unsigned cvt_pk_bf16(float lo, float hi) { unsigned r; asm volatile("v_cvt_pk_bf16_f32 %0, %1, %2" : "=v"(r) : "v"(lo), "v"(hi)); return r; }
; __device__ __forceinline__ float siluf_(float x) { return x * __builtin_amdgcn_rcpf(1.0f + __expf(-x)); }
; template <int MODE>
; __device__ __forceinline__ void ctx_small_gemm(PREF P, unsigned char* shm) {
;     ...
; #pragma unroll 4
;             for (int ks = 0; ks < KS; ++ks) {
;                 const bf16x8 a0 = *(const LAS bf16x8*)(lds + (rt0 * 16 + r) * (K * 2) + (((ks * 4 + q) ^ r) << 4));
;                 const bf16x8 b0 = *(const bf16x8*)(W0 + ks * 32);
;                 if (MODE == 0) { const bf16x8 b1 = *(const bf16x8*)(W1 + ks * 32);
;                     acc0 = __builtin_amdgcn_mfma_f32_16x16x32_bf16(a0, b0, acc0, 0, 0, 0); acc1 = __builtin_amdgcn_mfma_f32_16x16x32_bf16(a0, b1, acc1, 0, 0, 0); }
;                 else if (MODE == 3) { acc0 = __builtin_amdgcn_mfma_f32_16x16x32_bf16(a0, b0, acc0, 0, 0, 0); }
;     ...
;             } else if (MODE == 3) { bf16_t* CBo = (bf16_t*)(P.ws + O_CB); float zq3[4];
; #pragma unroll
;                 for (int i = 0; i < 4; ++i) { const int row = row_base + rt0 * 16 + q * 4 + i; zq3[i] = bf2f(parts[E_PZC + (size_t)row * 1024 + col]); }
; #pragma unroll
;                 for (int i = 0; i < 4; ++i) { const int row = row_base + rt0 * 16 + q * 4 + i; const float z = zq3[i];
;                     CBo[(size_t)row * 1024 + col] = (bf16_t)(cvt_pk_bf16(acc0[i] * siluf_(z), 0.f) & 0xffffu); }
	v_mfma_f32_16x16x32_bf16 v[2:5], v[192:195], v[96:99], v[2:5]
	ds_read_b128 v[192:195], v44 offset:3328
	s_waitcnt vmcnt(18) lgkmcnt(7)
	v_mfma_f32_16x16x32_bf16 v[2:5], v[196:199], v[100:103], v[2:5]
	ds_read_b128 v[196:199], v45 offset:3328
	s_waitcnt vmcnt(17) lgkmcnt(7)
	v_mfma_f32_16x16x32_bf16 v[2:5], v[200:203], v[104:107], v[2:5]
	ds_read_b128 v[200:203], v46 offset:3328
	s_waitcnt vmcnt(16) lgkmcnt(7)
	v_mfma_f32_16x16x32_bf16 v[2:5], v[204:207], v[108:111], v[2:5]
	ds_read_b128 v[204:207], v47 offset:3328
	s_waitcnt vmcnt(15) lgkmcnt(7)
	v_mfma_f32_16x16x32_bf16 v[2:5], v[176:179], v[112:115], v[2:5]
	ds_read_b128 v[176:179], v44 offset:3584
	s_waitcnt vmcnt(14) lgkmcnt(7)
	v_mfma_f32_16x16x32_bf16 v[2:5], v[180:183], v[116:119], v[2:5]
	ds_read_b128 v[180:183], v45 offset:3584
	s_waitcnt vmcnt(13) lgkmcnt(7)
	v_mfma_f32_16x16x32_bf16 v[2:5], v[184:187], v[120:123], v[2:5]
	ds_read_b128 v[184:187], v46 offset:3584
	s_waitcnt vmcnt(12) lgkmcnt(7)
	v_mfma_f32_16x16x32_bf16 v[2:5], v[188:191], v[124:127], v[2:5]
	ds_read_b128 v[188:191], v47 offset:3584
	s_waitcnt vmcnt(11) lgkmcnt(7)
	v_mfma_f32_16x16x32_bf16 v[2:5], v[192:195], v[128:131], v[2:5]
	ds_read_b128 v[192:195], v44 offset:3840
	s_waitcnt vmcnt(10) lgkmcnt(7)
	v_mfma_f32_16x16x32_bf16 v[2:5], v[196:199], v[132:135], v[2:5]
	ds_read_b128 v[196:199], v45 offset:3840
	s_waitcnt vmcnt(9) lgkmcnt(7)
	v_mfma_f32_16x16x32_bf16 v[2:5], v[200:203], v[136:139], v[2:5]
	ds_read_b128 v[200:203], v46 offset:3840
	s_waitcnt vmcnt(8) lgkmcnt(7)
	v_mfma_f32_16x16x32_bf16 v[2:5], v[204:207], v[140:143], v[2:5]
	ds_read_b128 v[204:207], v47 offset:3840
	s_waitcnt vmcnt(7) lgkmcnt(7)
	v_mfma_f32_16x16x32_bf16 v[2:5], v[176:179], v[144:147], v[2:5]
	s_waitcnt vmcnt(6) lgkmcnt(6)
	v_mfma_f32_16x16x32_bf16 v[2:5], v[180:183], v[148:151], v[2:5]
	s_waitcnt vmcnt(5) lgkmcnt(5)
	v_mfma_f32_16x16x32_bf16 v[2:5], v[184:187], v[152:155], v[2:5]
	s_waitcnt vmcnt(4) lgkmcnt(4)
	v_mfma_f32_16x16x32_bf16 v[2:5], v[188:191], v[156:159], v[2:5]
	s_waitcnt vmcnt(3) lgkmcnt(3)
	v_mfma_f32_16x16x32_bf16 v[2:5], v[192:195], v[160:163], v[2:5]
	s_waitcnt vmcnt(2) lgkmcnt(2)
	v_mfma_f32_16x16x32_bf16 v[2:5], v[196:199], v[164:167], v[2:5]
	s_waitcnt vmcnt(1) lgkmcnt(1)
	v_mfma_f32_16x16x32_bf16 v[2:5], v[200:203], v[168:171], v[2:5]
	s_waitcnt vmcnt(0) lgkmcnt(0)
	v_mfma_f32_16x16x32_bf16 v[2:5], v[204:207], v[172:175], v[2:5]
	s_movk_i32 s4, 0x100
	v_lshl_add_u64 v[10:11], s[16:17], 4, v[10:11]
	s_cmpk_eq_i32 s4, 0x100
	s_lshl_b32 s4, s0, 6
	s_and_b32 s4, s4, 0x3c0
	v_add_u32_e32 v10, s10, v15
	v_or_b32_e32 v6, s4, v16
	v_ashrrev_i32_e32 v11, 31, v10
	v_lshlrev_b32_e32 v6, 1, v6
	v_lshlrev_b64 v[20:21], 11, v[10:11]
	v_or_b32_e32 v24, 1, v10
	v_or_b32_e32 v28, 2, v10
	v_or_b32_e32 v10, 3, v10
	v_lshl_add_u64 v[18:19], s[14:15], 0, v[6:7]
	v_ashrrev_i32_e32 v25, 31, v24
	v_ashrrev_i32_e32 v29, 31, v28
	v_ashrrev_i32_e32 v11, 31, v10
	v_lshl_add_u64 v[22:23], v[18:19], 0, v[20:21]
	v_lshlrev_b64 v[24:25], 11, v[24:25]
	v_lshlrev_b64 v[28:29], 11, v[28:29]
	v_lshlrev_b64 v[10:11], 11, v[10:11]
	v_lshl_add_u64 v[26:27], v[18:19], 0, v[24:25]
	v_lshl_add_u64 v[30:31], v[18:19], 0, v[28:29]
	v_lshl_add_u64 v[18:19], v[18:19], 0, v[10:11]
	global_load_ushort v32, v[22:23], off
	global_load_ushort v33, v[26:27], off
	global_load_ushort v34, v[30:31], off
	global_load_ushort v35, v[18:19], off
	v_lshl_add_u64 v[18:19], s[12:13], 0, v[6:7]
	v_lshl_add_u64 v[20:21], v[18:19], 0, v[20:21]
	v_lshl_add_u64 v[22:23], v[18:19], 0, v[24:25]
	v_lshl_add_u64 v[24:25], v[18:19], 0, v[28:29]
	v_lshl_add_u64 v[10:11], v[18:19], 0, v[10:11]
	s_add_i32 s0, s0, s33
	s_add_i32 s1, s1, s2
	s_cmpk_gt_i32 s0, 0xff
	s_waitcnt vmcnt(3)
	v_lshlrev_b32_e32 v6, 16, v32
	v_mul_f32_e32 v27, 0xbfb8aa3b, v6
	s_waitcnt vmcnt(2)
	v_lshlrev_b32_e32 v18, 16, v33
	v_exp_f32_e32 v27, v27
	s_waitcnt vmcnt(1)
	v_lshlrev_b32_e32 v19, 16, v34
	v_mul_f32_e32 v28, 0xbfb8aa3b, v18
	s_waitcnt vmcnt(0)
	v_lshlrev_b32_e32 v26, 16, v35
	v_mul_f32_e32 v29, 0xbfb8aa3b, v19
	v_exp_f32_e32 v28, v28
	v_mul_f32_e32 v30, 0xbfb8aa3b, v26
	v_exp_f32_e32 v29, v29
	v_exp_f32_e32 v30, v30
	v_add_f32_e32 v27, 1.0, v27
	v_rcp_f32_e32 v27, v27
	v_add_f32_e32 v28, 1.0, v28
	v_add_f32_e32 v29, 1.0, v29
	v_rcp_f32_e32 v28, v28
	v_add_f32_e32 v30, 1.0, v30
	v_rcp_f32_e32 v29, v29
	v_rcp_f32_e32 v30, v30
	v_mul_f32_e32 v6, v27, v6
	v_mul_f32_e32 v2, v2, v6
	v_mul_f32_e32 v18, v28, v18
	v_cvt_pk_bf16_f32 v2, v2, v7
	v_mul_f32_e32 v19, v29, v19
	v_mul_f32_e32 v3, v3, v18
	global_store_short v[20:21], v2, off
	v_cvt_pk_bf16_f32 v2, v3, v7
	v_mul_f32_e32 v26, v30, v26
	v_mul_f32_e32 v4, v4, v19
	global_store_short v[22:23], v2, off
	v_cvt_pk_bf16_f32 v2, v4, v7
	v_mul_f32_e32 v5, v5, v26
	global_store_short v[24:25], v2, off
	v_cvt_pk_bf16_f32 v2, v5, v7
	global_store_short v[10:11], v2, off
	s_barrier
	s_cbranch_scc0 .LBB0_722

; #define LAS __attribute__((address_space(3)))
; template <int MODE>
; __device__ __forceinline__ void ctx_small_gemm(PREF P, unsigned char* shm) {
;     ...
;             for (int ks = 0; ks < KS; ++ks) {
;                 const bf16x8 a0 = *(const LAS bf16x8*)(lds + (rt0 * 16 + r) * (K * 2) + (((ks * 4 + q) ^ r) << 4));
;                 const bf16x8 b0 = *(const bf16x8*)(W0 + ks * 32);
;                 if (MODE == 0) { const bf16x8 b1 = *(const bf16x8*)(W1 + ks * 32);
;                     acc0 = __builtin_amdgcn_mfma_f32_16x16x32_bf16(a0, b0, acc0, 0, 0, 0); acc1 = __builtin_amdgcn_mfma_f32_16x16x32_bf16(a0, b1, acc1, 0, 0, 0); }
;                 else if (MODE == 3) { acc0 = __builtin_amdgcn_mfma_f32_16x16x32_bf16(a0, b0, acc0, 0, 0, 0); }
;                 else { const bf16x8 a1 = *(const LAS bf16x8*)(lds + (rt1 * 16 + r) * (K * 2) + (((ks * 4 + q) ^ r) << 4));
;                     acc0 = __builtin_amdgcn_mfma_f32_16x16x32_bf16(a0, b0, acc0, 0, 0, 0); acc1 = __builtin_amdgcn_mfma_f32_16x16x32_bf16(a1, b0, acc1, 0, 0, 0); }
.LBB0_828:
	v_xor_b32_e32 v134, v62, v25
	v_lshl_add_u32 v135, v134, 4, v63
	v_lshl_add_u32 v139, v134, 4, v64
	v_add_u32_e32 v134, 4, v62
	v_xor_b32_e32 v134, v134, v25
	v_lshl_add_u32 v136, v134, 4, v63
	v_lshl_add_u32 v140, v134, 4, v64
	v_add_u32_e32 v134, 8, v62
	v_xor_b32_e32 v134, v134, v25
	v_lshl_add_u32 v137, v134, 4, v63
	v_lshl_add_u32 v141, v134, 4, v64
	v_add_u32_e32 v134, 12, v62
	v_xor_b32_e32 v134, v134, v25
	v_lshl_add_u32 v138, v134, 4, v63
	v_lshl_add_u32 v142, v134, 4, v64
	global_load_dwordx4 v[144:147], v[60:61], off offset:-128
	global_load_dwordx4 v[148:151], v[60:61], off offset:-64
	global_load_dwordx4 v[152:155], v[60:61], off
	global_load_dwordx4 v[156:159], v[60:61], off offset:64
	global_load_dwordx4 v[160:163], v[60:61], off offset:128
	global_load_dwordx4 v[168:171], v[60:61], off offset:192
	global_load_dwordx4 v[172:175], v[60:61], off offset:256
	global_load_dwordx4 v[178:181], v[60:61], off offset:320
	global_load_dwordx4 v[182:185], v[60:61], off offset:384
	global_load_dwordx4 v[186:189], v[60:61], off offset:448
	global_load_dwordx4 v[190:193], v[60:61], off offset:512
	global_load_dwordx4 v[194:197], v[60:61], off offset:576
	global_load_dwordx4 v[198:201], v[60:61], off offset:640
	global_load_dwordx4 v[202:205], v[60:61], off offset:704
	global_load_dwordx4 v[206:209], v[60:61], off offset:768
	global_load_dwordx4 v[214:217], v[60:61], off offset:832
	ds_read_b128 v[218:221], v135
	ds_read_b128 v[222:225], v139
	ds_read_b128 v[226:229], v136
	ds_read_b128 v[230:233], v140
	ds_read_b128 v[234:237], v137
	ds_read_b128 v[238:241], v141
	ds_read_b128 v[242:245], v138
	ds_read_b128 v[246:249], v142
	s_waitcnt vmcnt(15) lgkmcnt(6)
	v_mfma_f32_16x16x32_bf16 v[2:5], v[218:221], v[144:147], v[2:5]
	v_mfma_f32_16x16x32_bf16 v[6:9], v[222:225], v[144:147], v[6:9]
	global_load_dwordx4 v[144:147], v[60:61], off offset:896
	ds_read_b128 v[218:221], v135 offset:256
	ds_read_b128 v[222:225], v139 offset:256
	s_waitcnt vmcnt(15) lgkmcnt(6)
	v_mfma_f32_16x16x32_bf16 v[2:5], v[226:229], v[148:151], v[2:5]
	v_mfma_f32_16x16x32_bf16 v[6:9], v[230:233], v[148:151], v[6:9]
	global_load_dwordx4 v[148:151], v[60:61], off offset:960
	ds_read_b128 v[226:229], v136 offset:256
	ds_read_b128 v[230:233], v140 offset:256
	s_waitcnt vmcnt(15) lgkmcnt(6)
	v_mfma_f32_16x16x32_bf16 v[2:5], v[234:237], v[152:155], v[2:5]
	v_mfma_f32_16x16x32_bf16 v[6:9], v[238:241], v[152:155], v[6:9]
	global_load_dwordx4 v[152:155], v[60:61], off offset:1024
	ds_read_b128 v[234:237], v137 offset:256
	ds_read_b128 v[238:241], v141 offset:256
	s_waitcnt vmcnt(15) lgkmcnt(6)
	v_mfma_f32_16x16x32_bf16 v[2:5], v[242:245], v[156:159], v[2:5]
	v_mfma_f32_16x16x32_bf16 v[6:9], v[246:249], v[156:159], v[6:9]
	global_load_dwordx4 v[156:159], v[60:61], off offset:1088
	ds_read_b128 v[242:245], v138 offset:256
	ds_read_b128 v[246:249], v142 offset:256
	s_waitcnt vmcnt(15) lgkmcnt(6)
	v_mfma_f32_16x16x32_bf16 v[2:5], v[218:221], v[160:163], v[2:5]
	v_mfma_f32_16x16x32_bf16 v[6:9], v[222:225], v[160:163], v[6:9]
	global_load_dwordx4 v[160:163], v[60:61], off offset:1152
	ds_read_b128 v[218:221], v135 offset:512
	ds_read_b128 v[222:225], v139 offset:512
	s_waitcnt vmcnt(15) lgkmcnt(6)
	v_mfma_f32_16x16x32_bf16 v[2:5], v[226:229], v[168:171], v[2:5]
	v_mfma_f32_16x16x32_bf16 v[6:9], v[230:233], v[168:171], v[6:9]
	global_load_dwordx4 v[168:171], v[60:61], off offset:1216
	ds_read_b128 v[226:229], v136 offset:512
	ds_read_b128 v[230:233], v140 offset:512
	s_waitcnt vmcnt(15) lgkmcnt(6)
	v_mfma_f32_16x16x32_bf16 v[2:5], v[234:237], v[172:175], v[2:5]
	v_mfma_f32_16x16x32_bf16 v[6:9], v[238:241], v[172:175], v[6:9]
	global_load_dwordx4 v[172:175], v[60:61], off offset:1280
	ds_read_b128 v[234:237], v137 offset:512
	ds_read_b128 v[238:241], v141 offset:512
	s_waitcnt vmcnt(15) lgkmcnt(6)
	v_mfma_f32_16x16x32_bf16 v[2:5], v[242:245], v[178:181], v[2:5]
	v_mfma_f32_16x16x32_bf16 v[6:9], v[246:249], v[178:181], v[6:9]
	global_load_dwordx4 v[178:181], v[60:61], off offset:1344
	ds_read_b128 v[242:245], v138 offset:512
	ds_read_b128 v[246:249], v142 offset:512
	s_waitcnt vmcnt(15) lgkmcnt(6)
	v_mfma_f32_16x16x32_bf16 v[2:5], v[218:221], v[182:185], v[2:5]
	v_mfma_f32_16x16x32_bf16 v[6:9], v[222:225], v[182:185], v[6:9]
	global_load_dwordx4 v[182:185], v[60:61], off offset:1408
	ds_read_b128 v[218:221], v135 offset:768
	ds_read_b128 v[222:225], v139 offset:768
	s_waitcnt vmcnt(15) lgkmcnt(6)
	v_mfma_f32_16x16x32_bf16 v[2:5], v[226:229], v[186:189], v[2:5]
	v_mfma_f32_16x16x32_bf16 v[6:9], v[230:233], v[186:189], v[6:9]
	global_load_dwordx4 v[186:189], v[60:61], off offset:1472
	ds_read_b128 v[226:229], v136 offset:768
	ds_read_b128 v[230:233], v140 offset:768
	s_waitcnt vmcnt(15) lgkmcnt(6)
	v_mfma_f32_16x16x32_bf16 v[2:5], v[234:237], v[190:193], v[2:5]
	v_mfma_f32_16x16x32_bf16 v[6:9], v[238:241], v[190:193], v[6:9]
	global_load_dwordx4 v[190:193], v[60:61], off offset:1536
	ds_read_b128 v[234:237], v137 offset:768
	ds_read_b128 v[238:241], v141 offset:768
	s_waitcnt vmcnt(15) lgkmcnt(6)
	v_mfma_f32_16x16x32_bf16 v[2:5], v[242:245], v[194:197], v[2:5]
	v_mfma_f32_16x16x32_bf16 v[6:9], v[246:249], v[194:197], v[6:9]
	global_load_dwordx4 v[194:197], v[60:61], off offset:1600
	ds_read_b128 v[242:245], v138 offset:768
	ds_read_b128 v[246:249], v142 offset:768
	s_waitcnt vmcnt(15) lgkmcnt(6)
	v_mfma_f32_16x16x32_bf16 v[2:5], v[218:221], v[198:201], v[2:5]
	v_mfma_f32_16x16x32_bf16 v[6:9], v[222:225], v[198:201], v[6:9]
	global_load_dwordx4 v[198:201], v[60:61], off offset:1664
	ds_read_b128 v[218:221], v135 offset:1024
	ds_read_b128 v[222:225], v139 offset:1024
	s_waitcnt vmcnt(15) lgkmcnt(6)
; #define LAS __attribute__((address_space(3)))
; __device__ __forceinline__ float bf2f(unsigned v) { return __uint_as_float(v << 16); }
; __device__ __forceinline__ float sigmoidf_(float x) { return __builtin_amdgcn_rcpf(1.0f + __expf(-x)); }
; template <int MODE>
; __device__ __forceinline__ void ctx_small_gemm(PREF P, unsigned char* shm) {
;     ...
;             for (int ks = 0; ks < KS; ++ks) {
;                 const bf16x8 a0 = *(const LAS bf16x8*)(lds + (rt0 * 16 + r) * (K * 2) + (((ks * 4 + q) ^ r) << 4));
;                 const bf16x8 b0 = *(const bf16x8*)(W0 + ks * 32);
;                 if (MODE == 0) { const bf16x8 b1 = *(const bf16x8*)(W1 + ks * 32);
;                     acc0 = __builtin_amdgcn_mfma_f32_16x16x32_bf16(a0, b0, acc0, 0, 0, 0); acc1 = __builtin_amdgcn_mfma_f32_16x16x32_bf16(a0, b1, acc1, 0, 0, 0); }
;                 else if (MODE == 3) { acc0 = __builtin_amdgcn_mfma_f32_16x16x32_bf16(a0, b0, acc0, 0, 0, 0); }
;                 else { const bf16x8 a1 = *(const LAS bf16x8*)(lds + (rt1 * 16 + r) * (K * 2) + (((ks * 4 + q) ^ r) << 4));
;                     acc0 = __builtin_amdgcn_mfma_f32_16x16x32_bf16(a0, b0, acc0, 0, 0, 0); acc1 = __builtin_amdgcn_mfma_f32_16x16x32_bf16(a1, b0, acc1, 0, 0, 0); }
;     ...
;                 for (int i = 0; i < 4; ++i) { const int rowa = row_base + rt0 * 16 + q * 4 + i, rowb = row_base + rt1 * 16 + q * 4 + i;
;                     msum[0][i] += acc0[i] * sigmoidf_(bf2f(parts[E_PGL + (size_t)rowa * 6144 + br * DM + col])); msum[1][i] += acc1[i] * sigmoidf_(bf2f(parts[E_PGL + (size_t)rowb * 6144 + br * DM + col])); }
	v_mfma_f32_16x16x32_bf16 v[2:5], v[226:229], v[202:205], v[2:5]
	v_mfma_f32_16x16x32_bf16 v[6:9], v[230:233], v[202:205], v[6:9]
	global_load_dwordx4 v[202:205], v[60:61], off offset:1728
	ds_read_b128 v[226:229], v136 offset:1024
	ds_read_b128 v[230:233], v140 offset:1024
	s_waitcnt vmcnt(15) lgkmcnt(6)
	v_mfma_f32_16x16x32_bf16 v[2:5], v[234:237], v[206:209], v[2:5]
	v_mfma_f32_16x16x32_bf16 v[6:9], v[238:241], v[206:209], v[6:9]
	global_load_dwordx4 v[206:209], v[60:61], off offset:1792
	ds_read_b128 v[234:237], v137 offset:1024
	ds_read_b128 v[238:241], v141 offset:1024
	s_waitcnt vmcnt(15) lgkmcnt(6)
	v_mfma_f32_16x16x32_bf16 v[2:5], v[242:245], v[214:217], v[2:5]
	v_mfma_f32_16x16x32_bf16 v[6:9], v[246:249], v[214:217], v[6:9]
	global_load_dwordx4 v[214:217], v[60:61], off offset:1856
	ds_read_b128 v[242:245], v138 offset:1024
	ds_read_b128 v[246:249], v142 offset:1024
	s_waitcnt vmcnt(15) lgkmcnt(6)
	v_mfma_f32_16x16x32_bf16 v[2:5], v[218:221], v[144:147], v[2:5]
	v_mfma_f32_16x16x32_bf16 v[6:9], v[222:225], v[144:147], v[6:9]
	ds_read_b128 v[218:221], v135 offset:1280
	ds_read_b128 v[222:225], v139 offset:1280
	s_waitcnt vmcnt(14) lgkmcnt(6)
	v_mfma_f32_16x16x32_bf16 v[2:5], v[226:229], v[148:151], v[2:5]
	v_mfma_f32_16x16x32_bf16 v[6:9], v[230:233], v[148:151], v[6:9]
	ds_read_b128 v[226:229], v136 offset:1280
	ds_read_b128 v[230:233], v140 offset:1280
	s_waitcnt vmcnt(13) lgkmcnt(6)
	v_mfma_f32_16x16x32_bf16 v[2:5], v[234:237], v[152:155], v[2:5]
	v_mfma_f32_16x16x32_bf16 v[6:9], v[238:241], v[152:155], v[6:9]
	ds_read_b128 v[234:237], v137 offset:1280
	ds_read_b128 v[238:241], v141 offset:1280
	s_waitcnt vmcnt(12) lgkmcnt(6)
	v_mfma_f32_16x16x32_bf16 v[2:5], v[242:245], v[156:159], v[2:5]
	v_mfma_f32_16x16x32_bf16 v[6:9], v[246:249], v[156:159], v[6:9]
	ds_read_b128 v[242:245], v138 offset:1280
	ds_read_b128 v[246:249], v142 offset:1280
	s_waitcnt vmcnt(11) lgkmcnt(6)
	v_mfma_f32_16x16x32_bf16 v[2:5], v[218:221], v[160:163], v[2:5]
	v_mfma_f32_16x16x32_bf16 v[6:9], v[222:225], v[160:163], v[6:9]
	ds_read_b128 v[218:221], v135 offset:1536
	ds_read_b128 v[222:225], v139 offset:1536
	s_waitcnt vmcnt(10) lgkmcnt(6)
	v_mfma_f32_16x16x32_bf16 v[2:5], v[226:229], v[168:171], v[2:5]
	v_mfma_f32_16x16x32_bf16 v[6:9], v[230:233], v[168:171], v[6:9]
	ds_read_b128 v[226:229], v136 offset:1536
	ds_read_b128 v[230:233], v140 offset:1536
	s_waitcnt vmcnt(9) lgkmcnt(6)
	v_mfma_f32_16x16x32_bf16 v[2:5], v[234:237], v[172:175], v[2:5]
	v_mfma_f32_16x16x32_bf16 v[6:9], v[238:241], v[172:175], v[6:9]
	ds_read_b128 v[234:237], v137 offset:1536
	ds_read_b128 v[238:241], v141 offset:1536
	s_waitcnt vmcnt(8) lgkmcnt(6)
	v_mfma_f32_16x16x32_bf16 v[2:5], v[242:245], v[178:181], v[2:5]
	v_mfma_f32_16x16x32_bf16 v[6:9], v[246:249], v[178:181], v[6:9]
	ds_read_b128 v[242:245], v138 offset:1536
	ds_read_b128 v[246:249], v142 offset:1536
	s_waitcnt vmcnt(7) lgkmcnt(6)
	v_mfma_f32_16x16x32_bf16 v[2:5], v[218:221], v[182:185], v[2:5]
	v_mfma_f32_16x16x32_bf16 v[6:9], v[222:225], v[182:185], v[6:9]
	ds_read_b128 v[218:221], v135 offset:1792
	ds_read_b128 v[222:225], v139 offset:1792
	s_waitcnt vmcnt(6) lgkmcnt(6)
	v_mfma_f32_16x16x32_bf16 v[2:5], v[226:229], v[186:189], v[2:5]
	v_mfma_f32_16x16x32_bf16 v[6:9], v[230:233], v[186:189], v[6:9]
	ds_read_b128 v[226:229], v136 offset:1792
	ds_read_b128 v[230:233], v140 offset:1792
	s_waitcnt vmcnt(5) lgkmcnt(6)
	v_mfma_f32_16x16x32_bf16 v[2:5], v[234:237], v[190:193], v[2:5]
	v_mfma_f32_16x16x32_bf16 v[6:9], v[238:241], v[190:193], v[6:9]
	ds_read_b128 v[234:237], v137 offset:1792
	ds_read_b128 v[238:241], v141 offset:1792
	s_waitcnt vmcnt(4) lgkmcnt(6)
	v_mfma_f32_16x16x32_bf16 v[2:5], v[242:245], v[194:197], v[2:5]
	v_mfma_f32_16x16x32_bf16 v[6:9], v[246:249], v[194:197], v[6:9]
	ds_read_b128 v[242:245], v138 offset:1792
	ds_read_b128 v[246:249], v142 offset:1792
	s_waitcnt vmcnt(3) lgkmcnt(6)
	v_mfma_f32_16x16x32_bf16 v[2:5], v[218:221], v[198:201], v[2:5]
	v_mfma_f32_16x16x32_bf16 v[6:9], v[222:225], v[198:201], v[6:9]
	s_waitcnt vmcnt(2) lgkmcnt(4)
	v_mfma_f32_16x16x32_bf16 v[2:5], v[226:229], v[202:205], v[2:5]
	v_mfma_f32_16x16x32_bf16 v[6:9], v[230:233], v[202:205], v[6:9]
	s_waitcnt vmcnt(1) lgkmcnt(2)
	v_mfma_f32_16x16x32_bf16 v[2:5], v[234:237], v[206:209], v[2:5]
	v_mfma_f32_16x16x32_bf16 v[6:9], v[238:241], v[206:209], v[6:9]
	s_waitcnt vmcnt(0) lgkmcnt(0)
	v_mfma_f32_16x16x32_bf16 v[2:5], v[242:245], v[214:217], v[2:5]
	v_mfma_f32_16x16x32_bf16 v[6:9], v[246:249], v[214:217], v[6:9]
	s_movk_i32 s4, 0x80
	v_lshl_add_u64 v[60:61], s[16:17], 3, v[60:61]
	s_cmpk_eq_i32 s4, 0x80
	s_lshl_b32 s18, s33, 12
	v_lshl_add_u64 v[60:61], v[36:37], 0, s[18:19]
	v_lshl_add_u64 v[70:71], v[38:39], 0, s[18:19]
	v_lshl_add_u64 v[72:73], v[42:43], 0, s[18:19]
	v_lshl_add_u64 v[74:75], v[46:47], 0, s[18:19]
	v_lshl_add_u64 v[76:77], v[48:49], 0, s[18:19]
	v_lshl_add_u64 v[78:79], v[52:53], 0, s[18:19]
	v_lshl_add_u64 v[80:81], v[56:57], 0, s[18:19]
	v_lshl_add_u64 v[82:83], v[58:59], 0, s[18:19]
	global_load_ushort v10, v[60:61], off
	global_load_ushort v69, v[70:71], off
	global_load_ushort v84, v[72:73], off
	global_load_ushort v85, v[74:75], off
	global_load_ushort v86, v[76:77], off
	global_load_ushort v87, v[78:79], off
	global_load_ushort v88, v[80:81], off
	global_load_ushort v89, v[82:83], off
	s_add_i32 s33, s33, 1
	s_cmp_eq_u32 s33, 3
	v_lshl_add_u64 v[18:19], v[18:19], 0, s[20:21]
	s_barrier
; __device__ __forceinline__ float bf2f(unsigned v) { return __uint_as_float(v << 16); }
; __device__ __forceinline__ unsigned cvt_pk_bf16(float lo, float hi) { unsigned r; asm volatile("v_cvt_pk_bf16_f32 %0, %1, %2" : "=v"(r) : "v"(lo), "v"(hi)); return r; }
; __device__ __forceinline__ float sigmoidf_(float x) { return __builtin_amdgcn_rcpf(1.0f + __expf(-x)); }
; template <int MODE>
; __device__ __forceinline__ void ctx_small_gemm(PREF P, unsigned char* shm) {
;     ...
;                 for (int i = 0; i < 4; ++i) { const int rowa = row_base + rt0 * 16 + q * 4 + i, rowb = row_base + rt1 * 16 + q * 4 + i;
;                     msum[0][i] += acc0[i] * sigmoidf_(bf2f(parts[E_PGL + (size_t)rowa * 6144 + br * DM + col])); msum[1][i] += acc1[i] * sigmoidf_(bf2f(parts[E_PGL + (size_t)rowb * 6144 + br * DM + col])); }
;     ...
;         if (MODE == 1) { bf16_t* MBo = (bf16_t*)(P.ws + O_HB); const int col = col0 + r;
; #pragma unroll
;             for (int i = 0; i < 4; ++i) { const int rowa = row_base + rt0 * 16 + q * 4 + i, rowb = row_base + rt1 * 16 + q * 4 + i;
;                 MBo[(size_t)rowa * DM + col] = (bf16_t)(cvt_pk_bf16(msum[0][i], 0.f) & 0xffffu); MBo[(size_t)rowb * DM + col] = (bf16_t)(cvt_pk_bf16(msum[1][i], 0.f) & 0xffffu); }
	s_waitcnt vmcnt(7)
	v_lshlrev_b32_e32 v10, 16, v10
	s_waitcnt vmcnt(6)
	v_lshlrev_b32_e32 v60, 16, v69
	s_waitcnt vmcnt(5)
	v_lshlrev_b32_e32 v61, 16, v84
	s_waitcnt vmcnt(4)
	v_lshlrev_b32_e32 v69, 16, v85
	s_waitcnt vmcnt(3)
	v_lshlrev_b32_e32 v70, 16, v86
	s_waitcnt vmcnt(2)
	v_lshlrev_b32_e32 v71, 16, v87
	s_waitcnt vmcnt(1)
	v_lshlrev_b32_e32 v72, 16, v88
	s_waitcnt vmcnt(0)
	v_lshlrev_b32_e32 v73, 16, v89
	v_mul_f32_e32 v10, 0xbfb8aa3b, v10
	v_mul_f32_e32 v60, 0xbfb8aa3b, v60
	v_mul_f32_e32 v61, 0xbfb8aa3b, v61
	v_mul_f32_e32 v69, 0xbfb8aa3b, v69
	v_mul_f32_e32 v70, 0xbfb8aa3b, v70
	v_mul_f32_e32 v71, 0xbfb8aa3b, v71
	v_mul_f32_e32 v72, 0xbfb8aa3b, v72
	v_mul_f32_e32 v73, 0xbfb8aa3b, v73
	v_exp_f32_e32 v10, v10
	v_exp_f32_e32 v60, v60
	v_exp_f32_e32 v61, v61
	v_exp_f32_e32 v69, v69
	v_exp_f32_e32 v70, v70
	v_exp_f32_e32 v71, v71
	v_exp_f32_e32 v72, v72
	v_exp_f32_e32 v73, v73
	v_add_f32_e32 v10, 1.0, v10
	v_add_f32_e32 v74, 1.0, v60
	v_add_f32_e32 v61, 1.0, v61
	v_add_f32_e32 v69, 1.0, v69
	v_add_f32_e32 v75, 1.0, v70
	v_add_f32_e32 v76, 1.0, v71
	v_add_f32_e32 v77, 1.0, v72
	v_add_f32_e32 v78, 1.0, v73
	v_rcp_f32_e32 v60, v10
	v_rcp_f32_e32 v70, v74
	v_rcp_f32_e32 v61, v61
	v_rcp_f32_e32 v71, v69
	v_rcp_f32_e32 v72, v75
	v_rcp_f32_e32 v74, v76
	v_rcp_f32_e32 v73, v77
	v_rcp_f32_e32 v75, v78
	v_pk_fma_f32 v[54:55], v[2:3], v[60:61], v[54:55]
	v_pk_fma_f32 v[50:51], v[6:7], v[70:71], v[50:51]
	v_pk_fma_f32 v[44:45], v[4:5], v[72:73], v[44:45]
	v_pk_fma_f32 v[40:41], v[8:9], v[74:75], v[40:41]
	s_cbranch_scc0 .LBB0_824
	v_lshlrev_b32_e32 v10, 1, v24
	v_lshl_add_u64 v[2:3], s[12:13], 0, v[10:11]
	v_lshlrev_b64 v[4:5], 12, v[20:21]
	v_lshl_add_u64 v[4:5], v[2:3], 0, v[4:5]
	v_cvt_pk_bf16_f32 v6, v54, v11
	global_store_short v[4:5], v6, off
	v_lshlrev_b64 v[4:5], 12, v[16:17]
	v_lshl_add_u64 v[4:5], v[2:3], 0, v[4:5]
	v_cvt_pk_bf16_f32 v6, v50, v11
	global_store_short v[4:5], v6, off
	v_lshlrev_b64 v[4:5], 12, v[26:27]
	v_lshl_add_u64 v[4:5], v[2:3], 0, v[4:5]
	v_cvt_pk_bf16_f32 v6, v55, v11
	global_store_short v[4:5], v6, off
	v_lshlrev_b64 v[4:5], 12, v[22:23]
	v_lshl_add_u64 v[4:5], v[2:3], 0, v[4:5]
	v_cvt_pk_bf16_f32 v6, v51, v11
	global_store_short v[4:5], v6, off
	v_lshlrev_b64 v[4:5], 12, v[30:31]
	v_lshl_add_u64 v[4:5], v[2:3], 0, v[4:5]
	v_cvt_pk_bf16_f32 v6, v44, v11
	global_store_short v[4:5], v6, off
	v_lshlrev_b64 v[4:5], 12, v[28:29]
	v_lshl_add_u64 v[4:5], v[2:3], 0, v[4:5]
	v_cvt_pk_bf16_f32 v6, v40, v11
	global_store_short v[4:5], v6, off
	v_lshlrev_b64 v[4:5], 12, v[34:35]
	v_lshl_add_u64 v[4:5], v[2:3], 0, v[4:5]
	v_cvt_pk_bf16_f32 v6, v45, v11
	global_store_short v[4:5], v6, off
	v_lshlrev_b64 v[4:5], 12, v[32:33]
	s_add_i32 s2, s2, s0
	s_add_i32 s11, s11, s28
	v_lshl_add_u64 v[2:3], v[2:3], 0, v[4:5]
	s_cmpk_gt_i32 s2, 0xff
	v_cvt_pk_bf16_f32 v6, v41, v11
	global_store_short v[2:3], v6, off
	s_cbranch_scc0 .LBB0_823

; #define LAS __attribute__((address_space(3)))
; template <int MODE>
; __device__ __forceinline__ void ctx_small_gemm(PREF P, unsigned char* shm) {
;     ...
;             for (int ks = 0; ks < KS; ++ks) {
;                 const bf16x8 a0 = *(const LAS bf16x8*)(lds + (rt0 * 16 + r) * (K * 2) + (((ks * 4 + q) ^ r) << 4));
;                 const bf16x8 b0 = *(const bf16x8*)(W0 + ks * 32);
;                 if (MODE == 0) { const bf16x8 b1 = *(const bf16x8*)(W1 + ks * 32);
;                     acc0 = __builtin_amdgcn_mfma_f32_16x16x32_bf16(a0, b0, acc0, 0, 0, 0); acc1 = __builtin_amdgcn_mfma_f32_16x16x32_bf16(a0, b1, acc1, 0, 0, 0); }
;                 else if (MODE == 3) { acc0 = __builtin_amdgcn_mfma_f32_16x16x32_bf16(a0, b0, acc0, 0, 0, 0); }
;                 else { const bf16x8 a1 = *(const LAS bf16x8*)(lds + (rt1 * 16 + r) * (K * 2) + (((ks * 4 + q) ^ r) << 4));
;                     acc0 = __builtin_amdgcn_mfma_f32_16x16x32_bf16(a0, b0, acc0, 0, 0, 0); acc1 = __builtin_amdgcn_mfma_f32_16x16x32_bf16(a1, b0, acc1, 0, 0, 0); }
.LBB0_940:
	v_xor_b32_e32 v53, v17, v16
	v_lshl_add_u32 v54, v53, 4, v19
	v_lshl_add_u32 v58, v53, 4, v20
	v_add_u32_e32 v53, 4, v17
	v_xor_b32_e32 v53, v53, v16
	v_lshl_add_u32 v55, v53, 4, v19
	v_lshl_add_u32 v59, v53, 4, v20
	v_add_u32_e32 v53, 8, v17
	v_xor_b32_e32 v53, v53, v16
	v_lshl_add_u32 v56, v53, 4, v19
	v_lshl_add_u32 v60, v53, 4, v20
	v_add_u32_e32 v53, 12, v17
	v_xor_b32_e32 v53, v53, v16
	v_lshl_add_u32 v57, v53, 4, v19
	v_lshl_add_u32 v61, v53, 4, v20
	global_load_dwordx4 v[62:65], v[14:15], off offset:-192
	global_load_dwordx4 v[66:69], v[14:15], off offset:-128
	global_load_dwordx4 v[70:73], v[14:15], off offset:-64
	global_load_dwordx4 v[74:77], v[14:15], off
	global_load_dwordx4 v[78:81], v[14:15], off offset:64
	global_load_dwordx4 v[82:85], v[14:15], off offset:128
	global_load_dwordx4 v[86:89], v[14:15], off offset:192
	global_load_dwordx4 v[90:93], v[14:15], off offset:256
	global_load_dwordx4 v[94:97], v[14:15], off offset:320
	global_load_dwordx4 v[98:101], v[14:15], off offset:384
	global_load_dwordx4 v[102:105], v[14:15], off offset:448
	global_load_dwordx4 v[106:109], v[14:15], off offset:512
	global_load_dwordx4 v[110:113], v[14:15], off offset:576
	global_load_dwordx4 v[114:117], v[14:15], off offset:640
	global_load_dwordx4 v[118:121], v[14:15], off offset:704
	global_load_dwordx4 v[122:125], v[14:15], off offset:768
	global_load_dwordx4 v[126:129], v[14:15], off offset:832
	global_load_dwordx4 v[130:133], v[14:15], off offset:896
	global_load_dwordx4 v[134:137], v[14:15], off offset:960
	global_load_dwordx4 v[138:141], v[14:15], off offset:1024
	global_load_dwordx4 v[142:145], v[14:15], off offset:1088
	global_load_dwordx4 v[146:149], v[14:15], off offset:1152
	global_load_dwordx4 v[150:153], v[14:15], off offset:1216
	global_load_dwordx4 v[154:157], v[14:15], off offset:1280
	global_load_dwordx4 v[158:161], v[14:15], off offset:1344
	global_load_dwordx4 v[162:165], v[14:15], off offset:1408
	global_load_dwordx4 v[166:169], v[14:15], off offset:1472
	global_load_dwordx4 v[170:173], v[14:15], off offset:1536
	ds_read_b128 v[174:177], v54
	ds_read_b128 v[178:181], v58
	ds_read_b128 v[182:185], v55
	ds_read_b128 v[186:189], v59
	ds_read_b128 v[190:193], v56
	ds_read_b128 v[194:197], v60
	ds_read_b128 v[198:201], v57
	ds_read_b128 v[202:205], v61
	ds_read_b128 v[206:209], v54 offset:256
	ds_read_b128 v[210:213], v58 offset:256
	ds_read_b128 v[214:217], v55 offset:256
	ds_read_b128 v[218:221], v59 offset:256
	ds_read_b128 v[222:225], v56 offset:256
	ds_read_b128 v[226:229], v60 offset:256
	ds_read_b128 v[230:233], v57 offset:256
	ds_read_b128 v[234:237], v61 offset:256
	s_waitcnt vmcnt(27) lgkmcnt(14)
	v_mfma_f32_16x16x32_bf16 v[6:9], v[174:177], v[62:65], v[6:9]
	v_mfma_f32_16x16x32_bf16 v[2:5], v[178:181], v[62:65], v[2:5]
	global_load_dwordx4 v[62:65], v[14:15], off offset:1600
	ds_read_b128 v[174:177], v54 offset:512
	ds_read_b128 v[178:181], v58 offset:512
	s_waitcnt vmcnt(27) lgkmcnt(14)
	v_mfma_f32_16x16x32_bf16 v[6:9], v[182:185], v[66:69], v[6:9]
	v_mfma_f32_16x16x32_bf16 v[2:5], v[186:189], v[66:69], v[2:5]
	global_load_dwordx4 v[66:69], v[14:15], off offset:1664
	ds_read_b128 v[182:185], v55 offset:512
	ds_read_b128 v[186:189], v59 offset:512
	s_waitcnt vmcnt(27) lgkmcnt(14)
	v_mfma_f32_16x16x32_bf16 v[6:9], v[190:193], v[70:73], v[6:9]
	v_mfma_f32_16x16x32_bf16 v[2:5], v[194:197], v[70:73], v[2:5]
	global_load_dwordx4 v[70:73], v[14:15], off offset:1728
	ds_read_b128 v[190:193], v56 offset:512
	ds_read_b128 v[194:197], v60 offset:512
	s_waitcnt vmcnt(27) lgkmcnt(14)
	v_mfma_f32_16x16x32_bf16 v[6:9], v[198:201], v[74:77], v[6:9]
	v_mfma_f32_16x16x32_bf16 v[2:5], v[202:205], v[74:77], v[2:5]
	global_load_dwordx4 v[74:77], v[14:15], off offset:1792
	ds_read_b128 v[198:201], v57 offset:512
	ds_read_b128 v[202:205], v61 offset:512
	s_waitcnt vmcnt(27) lgkmcnt(14)
	v_mfma_f32_16x16x32_bf16 v[6:9], v[206:209], v[78:81], v[6:9]
	v_mfma_f32_16x16x32_bf16 v[2:5], v[210:213], v[78:81], v[2:5]
	global_load_dwordx4 v[78:81], v[14:15], off offset:1856
	ds_read_b128 v[206:209], v54 offset:768
	ds_read_b128 v[210:213], v58 offset:768
	s_waitcnt vmcnt(27) lgkmcnt(14)
	v_mfma_f32_16x16x32_bf16 v[6:9], v[214:217], v[82:85], v[6:9]
	v_mfma_f32_16x16x32_bf16 v[2:5], v[218:221], v[82:85], v[2:5]
	global_load_dwordx4 v[82:85], v[14:15], off offset:1920
	ds_read_b128 v[214:217], v55 offset:768
	ds_read_b128 v[218:221], v59 offset:768
	s_waitcnt vmcnt(27) lgkmcnt(14)
	v_mfma_f32_16x16x32_bf16 v[6:9], v[222:225], v[86:89], v[6:9]
	v_mfma_f32_16x16x32_bf16 v[2:5], v[226:229], v[86:89], v[2:5]
	global_load_dwordx4 v[86:89], v[14:15], off offset:1984
	ds_read_b128 v[222:225], v56 offset:768
	ds_read_b128 v[226:229], v60 offset:768
	s_waitcnt vmcnt(27) lgkmcnt(14)
	v_mfma_f32_16x16x32_bf16 v[6:9], v[230:233], v[90:93], v[6:9]
	v_mfma_f32_16x16x32_bf16 v[2:5], v[234:237], v[90:93], v[2:5]
	global_load_dwordx4 v[90:93], v[14:15], off offset:2048
	ds_read_b128 v[230:233], v57 offset:768
	ds_read_b128 v[234:237], v61 offset:768
	s_waitcnt vmcnt(27) lgkmcnt(14)
	v_mfma_f32_16x16x32_bf16 v[6:9], v[174:177], v[94:97], v[6:9]
	v_mfma_f32_16x16x32_bf16 v[2:5], v[178:181], v[94:97], v[2:5]
	global_load_dwordx4 v[94:97], v[14:15], off offset:2112
	ds_read_b128 v[174:177], v54 offset:1024
	ds_read_b128 v[178:181], v58 offset:1024
	s_waitcnt vmcnt(27) lgkmcnt(14)
	v_mfma_f32_16x16x32_bf16 v[6:9], v[182:185], v[98:101], v[6:9]
	v_mfma_f32_16x16x32_bf16 v[2:5], v[186:189], v[98:101], v[2:5]
	global_load_dwordx4 v[98:101], v[14:15], off offset:2176
	ds_read_b128 v[182:185], v55 offset:1024
	ds_read_b128 v[186:189], v59 offset:1024
	s_waitcnt vmcnt(27) lgkmcnt(14)
; #define LAS __attribute__((address_space(3)))
; template <int MODE>
; __device__ __forceinline__ void ctx_small_gemm(PREF P, unsigned char* shm) {
;     ...
;             for (int ks = 0; ks < KS; ++ks) {
;                 const bf16x8 a0 = *(const LAS bf16x8*)(lds + (rt0 * 16 + r) * (K * 2) + (((ks * 4 + q) ^ r) << 4));
;                 const bf16x8 b0 = *(const bf16x8*)(W0 + ks * 32);
;                 if (MODE == 0) { const bf16x8 b1 = *(const bf16x8*)(W1 + ks * 32);
;                     acc0 = __builtin_amdgcn_mfma_f32_16x16x32_bf16(a0, b0, acc0, 0, 0, 0); acc1 = __builtin_amdgcn_mfma_f32_16x16x32_bf16(a0, b1, acc1, 0, 0, 0); }
;                 else if (MODE == 3) { acc0 = __builtin_amdgcn_mfma_f32_16x16x32_bf16(a0, b0, acc0, 0, 0, 0); }
;                 else { const bf16x8 a1 = *(const LAS bf16x8*)(lds + (rt1 * 16 + r) * (K * 2) + (((ks * 4 + q) ^ r) << 4));
;                     acc0 = __builtin_amdgcn_mfma_f32_16x16x32_bf16(a0, b0, acc0, 0, 0, 0); acc1 = __builtin_amdgcn_mfma_f32_16x16x32_bf16(a1, b0, acc1, 0, 0, 0); }
	v_mfma_f32_16x16x32_bf16 v[6:9], v[190:193], v[102:105], v[6:9]
	v_mfma_f32_16x16x32_bf16 v[2:5], v[194:197], v[102:105], v[2:5]
	global_load_dwordx4 v[102:105], v[14:15], off offset:2240
	ds_read_b128 v[190:193], v56 offset:1024
	ds_read_b128 v[194:197], v60 offset:1024
	s_waitcnt vmcnt(27) lgkmcnt(14)
	v_mfma_f32_16x16x32_bf16 v[6:9], v[198:201], v[106:109], v[6:9]
	v_mfma_f32_16x16x32_bf16 v[2:5], v[202:205], v[106:109], v[2:5]
	global_load_dwordx4 v[106:109], v[14:15], off offset:2304
	ds_read_b128 v[198:201], v57 offset:1024
	ds_read_b128 v[202:205], v61 offset:1024
	s_waitcnt vmcnt(27) lgkmcnt(14)
	v_mfma_f32_16x16x32_bf16 v[6:9], v[206:209], v[110:113], v[6:9]
	v_mfma_f32_16x16x32_bf16 v[2:5], v[210:213], v[110:113], v[2:5]
	global_load_dwordx4 v[110:113], v[14:15], off offset:2368
	ds_read_b128 v[206:209], v54 offset:1280
	ds_read_b128 v[210:213], v58 offset:1280
	s_waitcnt vmcnt(27) lgkmcnt(14)
	v_mfma_f32_16x16x32_bf16 v[6:9], v[214:217], v[114:117], v[6:9]
	v_mfma_f32_16x16x32_bf16 v[2:5], v[218:221], v[114:117], v[2:5]
	global_load_dwordx4 v[114:117], v[14:15], off offset:2432
	ds_read_b128 v[214:217], v55 offset:1280
	ds_read_b128 v[218:221], v59 offset:1280
	s_waitcnt vmcnt(27) lgkmcnt(14)
	v_mfma_f32_16x16x32_bf16 v[6:9], v[222:225], v[118:121], v[6:9]
	v_mfma_f32_16x16x32_bf16 v[2:5], v[226:229], v[118:121], v[2:5]
	global_load_dwordx4 v[118:121], v[14:15], off offset:2496
	ds_read_b128 v[222:225], v56 offset:1280
	ds_read_b128 v[226:229], v60 offset:1280
	s_waitcnt vmcnt(27) lgkmcnt(14)
	v_mfma_f32_16x16x32_bf16 v[6:9], v[230:233], v[122:125], v[6:9]
	v_mfma_f32_16x16x32_bf16 v[2:5], v[234:237], v[122:125], v[2:5]
	global_load_dwordx4 v[122:125], v[14:15], off offset:2560
	ds_read_b128 v[230:233], v57 offset:1280
	ds_read_b128 v[234:237], v61 offset:1280
	s_waitcnt vmcnt(27) lgkmcnt(14)
	v_mfma_f32_16x16x32_bf16 v[6:9], v[174:177], v[126:129], v[6:9]
	v_mfma_f32_16x16x32_bf16 v[2:5], v[178:181], v[126:129], v[2:5]
	global_load_dwordx4 v[126:129], v[14:15], off offset:2624
	ds_read_b128 v[174:177], v54 offset:1536
	ds_read_b128 v[178:181], v58 offset:1536
	s_waitcnt vmcnt(27) lgkmcnt(14)
	v_mfma_f32_16x16x32_bf16 v[6:9], v[182:185], v[130:133], v[6:9]
	v_mfma_f32_16x16x32_bf16 v[2:5], v[186:189], v[130:133], v[2:5]
	global_load_dwordx4 v[130:133], v[14:15], off offset:2688
	ds_read_b128 v[182:185], v55 offset:1536
	ds_read_b128 v[186:189], v59 offset:1536
	s_waitcnt vmcnt(27) lgkmcnt(14)
	v_mfma_f32_16x16x32_bf16 v[6:9], v[190:193], v[134:137], v[6:9]
	v_mfma_f32_16x16x32_bf16 v[2:5], v[194:197], v[134:137], v[2:5]
	global_load_dwordx4 v[134:137], v[14:15], off offset:2752
	ds_read_b128 v[190:193], v56 offset:1536
	ds_read_b128 v[194:197], v60 offset:1536
	s_waitcnt vmcnt(27) lgkmcnt(14)
	v_mfma_f32_16x16x32_bf16 v[6:9], v[198:201], v[138:141], v[6:9]
	v_mfma_f32_16x16x32_bf16 v[2:5], v[202:205], v[138:141], v[2:5]
	global_load_dwordx4 v[138:141], v[14:15], off offset:2816
	ds_read_b128 v[198:201], v57 offset:1536
	ds_read_b128 v[202:205], v61 offset:1536
	s_waitcnt vmcnt(27) lgkmcnt(14)
	v_mfma_f32_16x16x32_bf16 v[6:9], v[206:209], v[142:145], v[6:9]
	v_mfma_f32_16x16x32_bf16 v[2:5], v[210:213], v[142:145], v[2:5]
	global_load_dwordx4 v[142:145], v[14:15], off offset:2880
	ds_read_b128 v[206:209], v54 offset:1792
	ds_read_b128 v[210:213], v58 offset:1792
	s_waitcnt vmcnt(27) lgkmcnt(14)
	v_mfma_f32_16x16x32_bf16 v[6:9], v[214:217], v[146:149], v[6:9]
	v_mfma_f32_16x16x32_bf16 v[2:5], v[218:221], v[146:149], v[2:5]
	global_load_dwordx4 v[146:149], v[14:15], off offset:2944
	ds_read_b128 v[214:217], v55 offset:1792
	ds_read_b128 v[218:221], v59 offset:1792
	s_waitcnt vmcnt(27) lgkmcnt(14)
	v_mfma_f32_16x16x32_bf16 v[6:9], v[222:225], v[150:153], v[6:9]
	v_mfma_f32_16x16x32_bf16 v[2:5], v[226:229], v[150:153], v[2:5]
	global_load_dwordx4 v[150:153], v[14:15], off offset:3008
	ds_read_b128 v[222:225], v56 offset:1792
	ds_read_b128 v[226:229], v60 offset:1792
	s_waitcnt vmcnt(27) lgkmcnt(14)
	v_mfma_f32_16x16x32_bf16 v[6:9], v[230:233], v[154:157], v[6:9]
	v_mfma_f32_16x16x32_bf16 v[2:5], v[234:237], v[154:157], v[2:5]
	global_load_dwordx4 v[154:157], v[14:15], off offset:3072
	ds_read_b128 v[230:233], v57 offset:1792
	ds_read_b128 v[234:237], v61 offset:1792
	s_waitcnt vmcnt(27) lgkmcnt(14)
	v_mfma_f32_16x16x32_bf16 v[6:9], v[174:177], v[158:161], v[6:9]
	v_mfma_f32_16x16x32_bf16 v[2:5], v[178:181], v[158:161], v[2:5]
	global_load_dwordx4 v[158:161], v[14:15], off offset:3136
	ds_read_b128 v[174:177], v54 offset:2048
	ds_read_b128 v[178:181], v58 offset:2048
	s_waitcnt vmcnt(27) lgkmcnt(14)
	v_mfma_f32_16x16x32_bf16 v[6:9], v[182:185], v[162:165], v[6:9]
	v_mfma_f32_16x16x32_bf16 v[2:5], v[186:189], v[162:165], v[2:5]
	global_load_dwordx4 v[162:165], v[14:15], off offset:3200
	ds_read_b128 v[182:185], v55 offset:2048
	ds_read_b128 v[186:189], v59 offset:2048
	s_waitcnt vmcnt(27) lgkmcnt(14)
	v_mfma_f32_16x16x32_bf16 v[6:9], v[190:193], v[166:169], v[6:9]
	v_mfma_f32_16x16x32_bf16 v[2:5], v[194:197], v[166:169], v[2:5]
	global_load_dwordx4 v[166:169], v[14:15], off offset:3264
	ds_read_b128 v[190:193], v56 offset:2048
	ds_read_b128 v[194:197], v60 offset:2048
	s_waitcnt vmcnt(27) lgkmcnt(14)
	v_mfma_f32_16x16x32_bf16 v[6:9], v[198:201], v[170:173], v[6:9]
	v_mfma_f32_16x16x32_bf16 v[2:5], v[202:205], v[170:173], v[2:5]
	global_load_dwordx4 v[170:173], v[14:15], off offset:3328
	ds_read_b128 v[198:201], v57 offset:2048
	ds_read_b128 v[202:205], v61 offset:2048
	s_waitcnt vmcnt(27) lgkmcnt(14)
; #define LAS __attribute__((address_space(3)))
; template <int MODE>
; __device__ __forceinline__ void ctx_small_gemm(PREF P, unsigned char* shm) {
;     ...
;             for (int ks = 0; ks < KS; ++ks) {
;                 const bf16x8 a0 = *(const LAS bf16x8*)(lds + (rt0 * 16 + r) * (K * 2) + (((ks * 4 + q) ^ r) << 4));
;                 const bf16x8 b0 = *(const bf16x8*)(W0 + ks * 32);
;                 if (MODE == 0) { const bf16x8 b1 = *(const bf16x8*)(W1 + ks * 32);
;                     acc0 = __builtin_amdgcn_mfma_f32_16x16x32_bf16(a0, b0, acc0, 0, 0, 0); acc1 = __builtin_amdgcn_mfma_f32_16x16x32_bf16(a0, b1, acc1, 0, 0, 0); }
;                 else if (MODE == 3) { acc0 = __builtin_amdgcn_mfma_f32_16x16x32_bf16(a0, b0, acc0, 0, 0, 0); }
;                 else { const bf16x8 a1 = *(const LAS bf16x8*)(lds + (rt1 * 16 + r) * (K * 2) + (((ks * 4 + q) ^ r) << 4));
;                     acc0 = __builtin_amdgcn_mfma_f32_16x16x32_bf16(a0, b0, acc0, 0, 0, 0); acc1 = __builtin_amdgcn_mfma_f32_16x16x32_bf16(a1, b0, acc1, 0, 0, 0); }
	v_mfma_f32_16x16x32_bf16 v[6:9], v[206:209], v[62:65], v[6:9]
	v_mfma_f32_16x16x32_bf16 v[2:5], v[210:213], v[62:65], v[2:5]
	global_load_dwordx4 v[62:65], v[14:15], off offset:3392
	ds_read_b128 v[206:209], v54 offset:2304
	ds_read_b128 v[210:213], v58 offset:2304
	s_waitcnt vmcnt(27) lgkmcnt(14)
	v_mfma_f32_16x16x32_bf16 v[6:9], v[214:217], v[66:69], v[6:9]
	v_mfma_f32_16x16x32_bf16 v[2:5], v[218:221], v[66:69], v[2:5]
	global_load_dwordx4 v[66:69], v[14:15], off offset:3456
	ds_read_b128 v[214:217], v55 offset:2304
	ds_read_b128 v[218:221], v59 offset:2304
	s_waitcnt vmcnt(27) lgkmcnt(14)
	v_mfma_f32_16x16x32_bf16 v[6:9], v[222:225], v[70:73], v[6:9]
	v_mfma_f32_16x16x32_bf16 v[2:5], v[226:229], v[70:73], v[2:5]
	global_load_dwordx4 v[70:73], v[14:15], off offset:3520
	ds_read_b128 v[222:225], v56 offset:2304
	ds_read_b128 v[226:229], v60 offset:2304
	s_waitcnt vmcnt(27) lgkmcnt(14)
	v_mfma_f32_16x16x32_bf16 v[6:9], v[230:233], v[74:77], v[6:9]
	v_mfma_f32_16x16x32_bf16 v[2:5], v[234:237], v[74:77], v[2:5]
	global_load_dwordx4 v[74:77], v[14:15], off offset:3584
	ds_read_b128 v[230:233], v57 offset:2304
	ds_read_b128 v[234:237], v61 offset:2304
	s_waitcnt vmcnt(27) lgkmcnt(14)
	v_mfma_f32_16x16x32_bf16 v[6:9], v[174:177], v[78:81], v[6:9]
	v_mfma_f32_16x16x32_bf16 v[2:5], v[178:181], v[78:81], v[2:5]
	global_load_dwordx4 v[78:81], v[14:15], off offset:3648
	ds_read_b128 v[174:177], v54 offset:2560
	ds_read_b128 v[178:181], v58 offset:2560
	s_waitcnt vmcnt(27) lgkmcnt(14)
	v_mfma_f32_16x16x32_bf16 v[6:9], v[182:185], v[82:85], v[6:9]
	v_mfma_f32_16x16x32_bf16 v[2:5], v[186:189], v[82:85], v[2:5]
	global_load_dwordx4 v[82:85], v[14:15], off offset:3712
	ds_read_b128 v[182:185], v55 offset:2560
	ds_read_b128 v[186:189], v59 offset:2560
	s_waitcnt vmcnt(27) lgkmcnt(14)
	v_mfma_f32_16x16x32_bf16 v[6:9], v[190:193], v[86:89], v[6:9]
	v_mfma_f32_16x16x32_bf16 v[2:5], v[194:197], v[86:89], v[2:5]
	global_load_dwordx4 v[86:89], v[14:15], off offset:3776
	ds_read_b128 v[190:193], v56 offset:2560
	ds_read_b128 v[194:197], v60 offset:2560
	s_waitcnt vmcnt(27) lgkmcnt(14)
	v_mfma_f32_16x16x32_bf16 v[6:9], v[198:201], v[90:93], v[6:9]
	v_mfma_f32_16x16x32_bf16 v[2:5], v[202:205], v[90:93], v[2:5]
	global_load_dwordx4 v[90:93], v[14:15], off offset:3840
	ds_read_b128 v[198:201], v57 offset:2560
	ds_read_b128 v[202:205], v61 offset:2560
	s_waitcnt vmcnt(27) lgkmcnt(14)
	v_mfma_f32_16x16x32_bf16 v[6:9], v[206:209], v[94:97], v[6:9]
	v_mfma_f32_16x16x32_bf16 v[2:5], v[210:213], v[94:97], v[2:5]
	ds_read_b128 v[206:209], v54 offset:2816
	ds_read_b128 v[210:213], v58 offset:2816
	s_waitcnt vmcnt(26) lgkmcnt(14)
	v_mfma_f32_16x16x32_bf16 v[6:9], v[214:217], v[98:101], v[6:9]
	v_mfma_f32_16x16x32_bf16 v[2:5], v[218:221], v[98:101], v[2:5]
	ds_read_b128 v[214:217], v55 offset:2816
	ds_read_b128 v[218:221], v59 offset:2816
	s_waitcnt vmcnt(25) lgkmcnt(14)
	v_mfma_f32_16x16x32_bf16 v[6:9], v[222:225], v[102:105], v[6:9]
	v_mfma_f32_16x16x32_bf16 v[2:5], v[226:229], v[102:105], v[2:5]
	ds_read_b128 v[222:225], v56 offset:2816
	ds_read_b128 v[226:229], v60 offset:2816
	s_waitcnt vmcnt(24) lgkmcnt(14)
	v_mfma_f32_16x16x32_bf16 v[6:9], v[230:233], v[106:109], v[6:9]
	v_mfma_f32_16x16x32_bf16 v[2:5], v[234:237], v[106:109], v[2:5]
	ds_read_b128 v[230:233], v57 offset:2816
	ds_read_b128 v[234:237], v61 offset:2816
	s_waitcnt vmcnt(23) lgkmcnt(14)
	v_mfma_f32_16x16x32_bf16 v[6:9], v[174:177], v[110:113], v[6:9]
	v_mfma_f32_16x16x32_bf16 v[2:5], v[178:181], v[110:113], v[2:5]
	ds_read_b128 v[174:177], v54 offset:3072
	ds_read_b128 v[178:181], v58 offset:3072
	s_waitcnt vmcnt(22) lgkmcnt(14)
	v_mfma_f32_16x16x32_bf16 v[6:9], v[182:185], v[114:117], v[6:9]
	v_mfma_f32_16x16x32_bf16 v[2:5], v[186:189], v[114:117], v[2:5]
	ds_read_b128 v[182:185], v55 offset:3072
	ds_read_b128 v[186:189], v59 offset:3072
	s_waitcnt vmcnt(21) lgkmcnt(14)
	v_mfma_f32_16x16x32_bf16 v[6:9], v[190:193], v[118:121], v[6:9]
	v_mfma_f32_16x16x32_bf16 v[2:5], v[194:197], v[118:121], v[2:5]
	ds_read_b128 v[190:193], v56 offset:3072
	ds_read_b128 v[194:197], v60 offset:3072
	s_waitcnt vmcnt(20) lgkmcnt(14)
	v_mfma_f32_16x16x32_bf16 v[6:9], v[198:201], v[122:125], v[6:9]
	v_mfma_f32_16x16x32_bf16 v[2:5], v[202:205], v[122:125], v[2:5]
	ds_read_b128 v[198:201], v57 offset:3072
	ds_read_b128 v[202:205], v61 offset:3072
	s_waitcnt vmcnt(19) lgkmcnt(14)
	v_mfma_f32_16x16x32_bf16 v[6:9], v[206:209], v[126:129], v[6:9]
	v_mfma_f32_16x16x32_bf16 v[2:5], v[210:213], v[126:129], v[2:5]
	ds_read_b128 v[206:209], v54 offset:3328
	ds_read_b128 v[210:213], v58 offset:3328
	s_waitcnt vmcnt(18) lgkmcnt(14)
	v_mfma_f32_16x16x32_bf16 v[6:9], v[214:217], v[130:133], v[6:9]
	v_mfma_f32_16x16x32_bf16 v[2:5], v[218:221], v[130:133], v[2:5]
	ds_read_b128 v[214:217], v55 offset:3328
	ds_read_b128 v[218:221], v59 offset:3328
	s_waitcnt vmcnt(17) lgkmcnt(14)
	v_mfma_f32_16x16x32_bf16 v[6:9], v[222:225], v[134:137], v[6:9]
	v_mfma_f32_16x16x32_bf16 v[2:5], v[226:229], v[134:137], v[2:5]
	ds_read_b128 v[222:225], v56 offset:3328
	ds_read_b128 v[226:229], v60 offset:3328
	s_waitcnt vmcnt(16) lgkmcnt(14)
	v_mfma_f32_16x16x32_bf16 v[6:9], v[230:233], v[138:141], v[6:9]
	v_mfma_f32_16x16x32_bf16 v[2:5], v[234:237], v[138:141], v[2:5]
	ds_read_b128 v[230:233], v57 offset:3328
	ds_read_b128 v[234:237], v61 offset:3328
	s_waitcnt vmcnt(15) lgkmcnt(14)
; #define LAS __attribute__((address_space(3)))
; __device__ __forceinline__ unsigned cvt_pk_bf16(float lo, float hi) { unsigned r; asm volatile("v_cvt_pk_bf16_f32 %0, %1, %2" : "=v"(r) : "v"(lo), "v"(hi)); return r; }
; template <int MODE>
; __device__ __forceinline__ void ctx_small_gemm(PREF P, unsigned char* shm) {
;     ...
;             for (int ks = 0; ks < KS; ++ks) {
;                 const bf16x8 a0 = *(const LAS bf16x8*)(lds + (rt0 * 16 + r) * (K * 2) + (((ks * 4 + q) ^ r) << 4));
;                 const bf16x8 b0 = *(const bf16x8*)(W0 + ks * 32);
;                 if (MODE == 0) { const bf16x8 b1 = *(const bf16x8*)(W1 + ks * 32);
;                     acc0 = __builtin_amdgcn_mfma_f32_16x16x32_bf16(a0, b0, acc0, 0, 0, 0); acc1 = __builtin_amdgcn_mfma_f32_16x16x32_bf16(a0, b1, acc1, 0, 0, 0); }
;                 else if (MODE == 3) { acc0 = __builtin_amdgcn_mfma_f32_16x16x32_bf16(a0, b0, acc0, 0, 0, 0); }
;                 else { const bf16x8 a1 = *(const LAS bf16x8*)(lds + (rt1 * 16 + r) * (K * 2) + (((ks * 4 + q) ^ r) << 4));
;                     acc0 = __builtin_amdgcn_mfma_f32_16x16x32_bf16(a0, b0, acc0, 0, 0, 0); acc1 = __builtin_amdgcn_mfma_f32_16x16x32_bf16(a1, b0, acc1, 0, 0, 0); }
;     ...
;             } else { bf16_t* OBo = (bf16_t*)(P.ws + O_PARTS);
; #pragma unroll
;                 for (int i = 0; i < 4; ++i) { const int rowa = row_base + rt0 * 16 + q * 4 + i, rowb = row_base + rt1 * 16 + q * 4 + i;
;                     OBo[(size_t)rowa * DM + col] = (bf16_t)(cvt_pk_bf16(acc0[i], 0.f) & 0xffffu); OBo[(size_t)rowb * DM + col] = (bf16_t)(cvt_pk_bf16(acc1[i], 0.f) & 0xffffu); }
	v_mfma_f32_16x16x32_bf16 v[6:9], v[174:177], v[142:145], v[6:9]
	v_mfma_f32_16x16x32_bf16 v[2:5], v[178:181], v[142:145], v[2:5]
	ds_read_b128 v[174:177], v54 offset:3584
	ds_read_b128 v[178:181], v58 offset:3584
	s_waitcnt vmcnt(14) lgkmcnt(14)
	v_mfma_f32_16x16x32_bf16 v[6:9], v[182:185], v[146:149], v[6:9]
	v_mfma_f32_16x16x32_bf16 v[2:5], v[186:189], v[146:149], v[2:5]
	ds_read_b128 v[182:185], v55 offset:3584
	ds_read_b128 v[186:189], v59 offset:3584
	s_waitcnt vmcnt(13) lgkmcnt(14)
	v_mfma_f32_16x16x32_bf16 v[6:9], v[190:193], v[150:153], v[6:9]
	v_mfma_f32_16x16x32_bf16 v[2:5], v[194:197], v[150:153], v[2:5]
	ds_read_b128 v[190:193], v56 offset:3584
	ds_read_b128 v[194:197], v60 offset:3584
	s_waitcnt vmcnt(12) lgkmcnt(14)
	v_mfma_f32_16x16x32_bf16 v[6:9], v[198:201], v[154:157], v[6:9]
	v_mfma_f32_16x16x32_bf16 v[2:5], v[202:205], v[154:157], v[2:5]
	ds_read_b128 v[198:201], v57 offset:3584
	ds_read_b128 v[202:205], v61 offset:3584
	s_waitcnt vmcnt(11) lgkmcnt(14)
	v_mfma_f32_16x16x32_bf16 v[6:9], v[206:209], v[158:161], v[6:9]
	v_mfma_f32_16x16x32_bf16 v[2:5], v[210:213], v[158:161], v[2:5]
	ds_read_b128 v[206:209], v54 offset:3840
	ds_read_b128 v[210:213], v58 offset:3840
	s_waitcnt vmcnt(10) lgkmcnt(14)
	v_mfma_f32_16x16x32_bf16 v[6:9], v[214:217], v[162:165], v[6:9]
	v_mfma_f32_16x16x32_bf16 v[2:5], v[218:221], v[162:165], v[2:5]
	ds_read_b128 v[214:217], v55 offset:3840
	ds_read_b128 v[218:221], v59 offset:3840
	s_waitcnt vmcnt(9) lgkmcnt(14)
	v_mfma_f32_16x16x32_bf16 v[6:9], v[222:225], v[166:169], v[6:9]
	v_mfma_f32_16x16x32_bf16 v[2:5], v[226:229], v[166:169], v[2:5]
	ds_read_b128 v[222:225], v56 offset:3840
	ds_read_b128 v[226:229], v60 offset:3840
	s_waitcnt vmcnt(8) lgkmcnt(14)
	v_mfma_f32_16x16x32_bf16 v[6:9], v[230:233], v[170:173], v[6:9]
	v_mfma_f32_16x16x32_bf16 v[2:5], v[234:237], v[170:173], v[2:5]
	ds_read_b128 v[230:233], v57 offset:3840
	ds_read_b128 v[234:237], v61 offset:3840
	s_waitcnt vmcnt(7) lgkmcnt(14)
	v_mfma_f32_16x16x32_bf16 v[6:9], v[174:177], v[62:65], v[6:9]
	v_mfma_f32_16x16x32_bf16 v[2:5], v[178:181], v[62:65], v[2:5]
	s_waitcnt vmcnt(6) lgkmcnt(12)
	v_mfma_f32_16x16x32_bf16 v[6:9], v[182:185], v[66:69], v[6:9]
	v_mfma_f32_16x16x32_bf16 v[2:5], v[186:189], v[66:69], v[2:5]
	s_waitcnt vmcnt(5) lgkmcnt(10)
	v_mfma_f32_16x16x32_bf16 v[6:9], v[190:193], v[70:73], v[6:9]
	v_mfma_f32_16x16x32_bf16 v[2:5], v[194:197], v[70:73], v[2:5]
	s_waitcnt vmcnt(4) lgkmcnt(8)
	v_mfma_f32_16x16x32_bf16 v[6:9], v[198:201], v[74:77], v[6:9]
	v_mfma_f32_16x16x32_bf16 v[2:5], v[202:205], v[74:77], v[2:5]
	s_waitcnt vmcnt(3) lgkmcnt(6)
	v_mfma_f32_16x16x32_bf16 v[6:9], v[206:209], v[78:81], v[6:9]
	v_mfma_f32_16x16x32_bf16 v[2:5], v[210:213], v[78:81], v[2:5]
	s_waitcnt vmcnt(2) lgkmcnt(4)
	v_mfma_f32_16x16x32_bf16 v[6:9], v[214:217], v[82:85], v[6:9]
	v_mfma_f32_16x16x32_bf16 v[2:5], v[218:221], v[82:85], v[2:5]
	s_waitcnt vmcnt(1) lgkmcnt(2)
	v_mfma_f32_16x16x32_bf16 v[6:9], v[222:225], v[86:89], v[6:9]
	v_mfma_f32_16x16x32_bf16 v[2:5], v[226:229], v[86:89], v[2:5]
	s_waitcnt vmcnt(0) lgkmcnt(0)
	v_mfma_f32_16x16x32_bf16 v[6:9], v[230:233], v[90:93], v[6:9]
	v_mfma_f32_16x16x32_bf16 v[2:5], v[234:237], v[90:93], v[2:5]
	s_movk_i32 s4, 0x100
	v_lshl_add_u64 v[14:15], s[14:15], 4, v[14:15]
	s_cmpk_eq_i32 s4, 0x100
	s_lshl_b32 s4, s2, 7
	s_and_b32 s4, s4, 0x780
	v_add_u32_e32 v14, s4, v18
	v_or_b32_e32 v24, s21, v21
	v_ashrrev_i32_e32 v15, 31, v14
	v_ashrrev_i32_e32 v25, 31, v24
	v_add_u32_e32 v26, s20, v22
	v_lshl_add_u64 v[14:15], v[14:15], 1, s[12:13]
	v_lshlrev_b64 v[28:29], 12, v[24:25]
	v_lshl_add_u64 v[28:29], v[14:15], 0, v[28:29]
	v_ashrrev_i32_e32 v27, 31, v26
	v_cvt_pk_bf16_f32 v6, v6, v11
	global_store_short v[28:29], v6, off
	v_lshlrev_b64 v[28:29], 12, v[26:27]
	v_lshl_add_u64 v[28:29], v[14:15], 0, v[28:29]
	v_or_b32_e32 v6, 1, v24
	v_cvt_pk_bf16_f32 v2, v2, v11
	global_store_short v[28:29], v2, off
	v_cvt_pk_bf16_f32 v10, v7, v11
	v_ashrrev_i32_e32 v7, 31, v6
	v_lshlrev_b64 v[6:7], 12, v[6:7]
	v_or_b32_e32 v2, 1, v26
	v_lshl_add_u64 v[6:7], v[14:15], 0, v[6:7]
	global_store_short v[6:7], v10, off
	v_cvt_pk_bf16_f32 v6, v3, v11
	v_ashrrev_i32_e32 v3, 31, v2
	v_lshlrev_b64 v[2:3], 12, v[2:3]
	v_lshl_add_u64 v[2:3], v[14:15], 0, v[2:3]
	global_store_short v[2:3], v6, off
	v_or_b32_e32 v2, 2, v24
	v_ashrrev_i32_e32 v3, 31, v2
	v_lshlrev_b64 v[2:3], 12, v[2:3]
	v_or_b32_e32 v6, 2, v26
	v_cvt_pk_bf16_f32 v7, v8, v11
	v_lshl_add_u64 v[2:3], v[14:15], 0, v[2:3]
	global_store_short v[2:3], v7, off
	v_ashrrev_i32_e32 v7, 31, v6
	v_lshlrev_b64 v[2:3], 12, v[6:7]
	v_lshl_add_u64 v[2:3], v[14:15], 0, v[2:3]
	v_cvt_pk_bf16_f32 v4, v4, v11
	global_store_short v[2:3], v4, off
	v_or_b32_e32 v2, 3, v24
	v_ashrrev_i32_e32 v3, 31, v2
	v_lshlrev_b64 v[2:3], 12, v[2:3]
	v_or_b32_e32 v4, 3, v26
	v_cvt_pk_bf16_f32 v6, v9, v11
	v_lshl_add_u64 v[2:3], v[14:15], 0, v[2:3]
	global_store_short v[2:3], v6, off
	v_cvt_pk_bf16_f32 v6, v5, v11
	v_ashrrev_i32_e32 v5, 31, v4
	v_lshlrev_b64 v[2:3], 12, v[4:5]
	s_add_i32 s2, s2, s0
	s_add_i32 s3, s3, s10
	v_lshl_add_u64 v[2:3], v[14:15], 0, v[2:3]
	s_cmpk_gt_i32 s2, 0xff
	global_store_short v[2:3], v6, off
	s_barrier
	s_cbranch_scc0 .LBB0_936
